# v48 + GEMM K-loops: loop counter/address SALU block moved above the closing barrier (back-edge rotation, 7.11)
# baseline (speedup 1.0000x reference)
.LBB0_220:
	ds_read_b128 v[148:151], v173
	ds_read_b128 v[152:155], v173 offset:1024
	ds_read_b128 v[156:159], v173 offset:2048
	ds_read_b128 v[160:163], v173 offset:3072
	ds_read_b128 v[164:167], v174
	ds_read_b128 v[180:183], v174 offset:1024
	ds_read_b128 v[184:187], v174 offset:2048
	ds_read_b128 v[188:191], v174 offset:3072
	s_add_u32 s52, s50, 0xfffc0080
	s_addc_u32 s53, s51, -1
	s_cmp_eq_u32 s66, 12
	s_cselect_b32 s55, s9, s53
	s_cselect_b32 s54, s11, s52
	s_cselect_b32 s53, s20, s45
	s_cselect_b32 s52, s33, s43
	v_lshl_add_u64 v[168:169], s[50:51], 0, v[140:141]
	s_add_i32 m0, s35, 0xc000
	ds_read_b128 v[192:195], v175
	ds_read_b128 v[196:199], v175 offset:1024
	ds_read_b128 v[204:207], v175 offset:2048
	ds_read_b128 v[208:211], v175 offset:3072
	ds_read_b128 v[212:215], v175 offset:4096
	ds_read_b128 v[216:219], v175 offset:5120
	ds_read_b128 v[220:223], v175 offset:6144
	ds_read_b128 v[224:227], v175 offset:7168
	global_load_lds_dwordx4 v[168:169], off
	v_lshl_add_u64 v[168:169], s[50:51], 0, v[142:143]
	s_add_i32 m0, s35, 0xe000
	s_nop 0
	global_load_lds_dwordx4 v[168:169], off
	s_waitcnt vmcnt(8)
	s_waitcnt lgkmcnt(0)
	s_barrier
	s_setprio 1
	s_waitcnt lgkmcnt(0)
	v_mfma_f32_16x16x32_bf16 v[124:127], v[148:151], v[192:195], v[124:127]
	v_mfma_f32_16x16x32_bf16 v[120:123], v[156:159], v[192:195], v[120:123]
	v_mfma_f32_16x16x32_bf16 v[108:111], v[148:151], v[204:207], v[108:111]
	v_mfma_f32_16x16x32_bf16 v[104:107], v[156:159], v[204:207], v[104:107]
	v_mfma_f32_16x16x32_bf16 v[92:95], v[148:151], v[212:215], v[92:95]
	v_mfma_f32_16x16x32_bf16 v[88:91], v[156:159], v[212:215], v[88:91]
	v_mfma_f32_16x16x32_bf16 v[76:79], v[148:151], v[220:223], v[76:79]
	v_mfma_f32_16x16x32_bf16 v[72:75], v[156:159], v[220:223], v[72:75]
	v_mfma_f32_16x16x32_bf16 v[124:127], v[152:155], v[196:199], v[124:127]
	v_mfma_f32_16x16x32_bf16 v[120:123], v[160:163], v[196:199], v[120:123]
	v_mfma_f32_16x16x32_bf16 v[108:111], v[152:155], v[208:211], v[108:111]
	v_mfma_f32_16x16x32_bf16 v[104:107], v[160:163], v[208:211], v[104:107]
	v_mfma_f32_16x16x32_bf16 v[92:95], v[152:155], v[216:219], v[92:95]
	v_mfma_f32_16x16x32_bf16 v[88:91], v[160:163], v[216:219], v[88:91]
	v_mfma_f32_16x16x32_bf16 v[76:79], v[152:155], v[224:227], v[76:79]
	v_mfma_f32_16x16x32_bf16 v[72:75], v[160:163], v[224:227], v[72:75]
	s_setprio 0
	s_setprio 1
	v_mfma_f32_16x16x32_bf16 v[116:119], v[164:167], v[192:195], v[116:119]
	v_mfma_f32_16x16x32_bf16 v[112:115], v[184:187], v[192:195], v[112:115]
	v_mfma_f32_16x16x32_bf16 v[100:103], v[164:167], v[204:207], v[100:103]
	v_mfma_f32_16x16x32_bf16 v[96:99], v[184:187], v[204:207], v[96:99]
	v_mfma_f32_16x16x32_bf16 v[84:87], v[164:167], v[212:215], v[84:87]
	v_mfma_f32_16x16x32_bf16 v[80:83], v[184:187], v[212:215], v[80:83]
	v_mfma_f32_16x16x32_bf16 v[68:71], v[164:167], v[220:223], v[68:71]
	v_mfma_f32_16x16x32_bf16 v[64:67], v[184:187], v[220:223], v[64:67]
	v_mfma_f32_16x16x32_bf16 v[116:119], v[180:183], v[196:199], v[116:119]
	v_mfma_f32_16x16x32_bf16 v[112:115], v[188:191], v[196:199], v[112:115]
	v_mfma_f32_16x16x32_bf16 v[100:103], v[180:183], v[208:211], v[100:103]
	v_mfma_f32_16x16x32_bf16 v[96:99], v[188:191], v[208:211], v[96:99]
	v_mfma_f32_16x16x32_bf16 v[84:87], v[180:183], v[216:219], v[84:87]
	v_mfma_f32_16x16x32_bf16 v[80:83], v[188:191], v[216:219], v[80:83]
	v_mfma_f32_16x16x32_bf16 v[68:71], v[180:183], v[224:227], v[68:71]
	v_mfma_f32_16x16x32_bf16 v[64:67], v[188:191], v[224:227], v[64:67]
	s_setprio 0
	s_barrier
	s_add_i32 s67, s63, s31
	v_lshl_add_u64 v[168:169], s[52:53], 0, v[130:131]
	s_mov_b32 m0, s67
	ds_read_b128 v[192:195], v175 offset:16384
	ds_read_b128 v[196:199], v175 offset:17408
	ds_read_b128 v[204:207], v175 offset:18432
	ds_read_b128 v[208:211], v175 offset:19456
	ds_read_b128 v[212:215], v175 offset:20480
	ds_read_b128 v[216:219], v175 offset:21504
	ds_read_b128 v[220:223], v175 offset:22528
	ds_read_b128 v[224:227], v175 offset:23552
	global_load_lds_dwordx4 v[168:169], off
	s_add_i32 m0, s67, 0x2000
	s_add_u32 s68, s52, 0x40000
	v_lshl_add_u64 v[200:201], s[52:53], 0, v[134:135]
	s_addc_u32 s69, s53, 0
	s_add_i32 s67, s64, s31
	global_load_lds_dwordx4 v[200:201], off
	v_lshl_add_u64 v[228:229], s[68:69], 0, v[130:131]
	s_mov_b32 m0, s67
	v_lshl_add_u64 v[230:231], s[54:55], 0, v[132:133]
	global_load_lds_dwordx4 v[228:229], off
	v_lshl_add_u64 v[228:229], s[68:69], 0, v[134:135]
	s_add_i32 m0, s67, 0x2000
	s_nop 0
	global_load_lds_dwordx4 v[228:229], off
	v_lshl_add_u64 v[228:229], s[54:55], 0, v[128:129]
	s_mov_b32 m0, s35
	s_nop 0
	global_load_lds_dwordx4 v[228:229], off
	s_mov_b32 m0, s37
	s_nop 0
	global_load_lds_dwordx4 v[230:231], off
	s_waitcnt vmcnt(8)
	s_waitcnt lgkmcnt(0)
	s_barrier
	s_setprio 1
	s_waitcnt lgkmcnt(0)
	v_mfma_f32_16x16x32_bf16 v[60:63], v[148:151], v[192:195], v[60:63]
	v_mfma_f32_16x16x32_bf16 v[56:59], v[156:159], v[192:195], v[56:59]
	v_mfma_f32_16x16x32_bf16 v[44:47], v[148:151], v[204:207], v[44:47]
	v_mfma_f32_16x16x32_bf16 v[40:43], v[156:159], v[204:207], v[40:43]
	v_mfma_f32_16x16x32_bf16 v[28:31], v[148:151], v[212:215], v[28:31]
	v_mfma_f32_16x16x32_bf16 v[24:27], v[156:159], v[212:215], v[24:27]
	v_mfma_f32_16x16x32_bf16 v[12:15], v[148:151], v[220:223], v[12:15]
	v_mfma_f32_16x16x32_bf16 v[8:11], v[156:159], v[220:223], v[8:11]
	v_mfma_f32_16x16x32_bf16 v[60:63], v[152:155], v[196:199], v[60:63]
	v_mfma_f32_16x16x32_bf16 v[56:59], v[160:163], v[196:199], v[56:59]
	v_mfma_f32_16x16x32_bf16 v[44:47], v[152:155], v[208:211], v[44:47]
	v_mfma_f32_16x16x32_bf16 v[40:43], v[160:163], v[208:211], v[40:43]
	v_mfma_f32_16x16x32_bf16 v[28:31], v[152:155], v[216:219], v[28:31]
	v_mfma_f32_16x16x32_bf16 v[24:27], v[160:163], v[216:219], v[24:27]
	v_mfma_f32_16x16x32_bf16 v[12:15], v[152:155], v[224:227], v[12:15]
	v_mfma_f32_16x16x32_bf16 v[8:11], v[160:163], v[224:227], v[8:11]
	s_setprio 0
	s_setprio 1
	v_mfma_f32_16x16x32_bf16 v[52:55], v[164:167], v[192:195], v[52:55]
	v_mfma_f32_16x16x32_bf16 v[48:51], v[184:187], v[192:195], v[48:51]
	v_mfma_f32_16x16x32_bf16 v[36:39], v[164:167], v[204:207], v[36:39]
	v_mfma_f32_16x16x32_bf16 v[32:35], v[184:187], v[204:207], v[32:35]
	v_mfma_f32_16x16x32_bf16 v[20:23], v[164:167], v[212:215], v[20:23]
	v_mfma_f32_16x16x32_bf16 v[16:19], v[184:187], v[212:215], v[16:19]
	v_mfma_f32_16x16x32_bf16 v[4:7], v[164:167], v[220:223], v[4:7]
	v_mfma_f32_16x16x32_bf16 v[0:3], v[184:187], v[220:223], v[0:3]
	v_mfma_f32_16x16x32_bf16 v[52:55], v[180:183], v[196:199], v[52:55]
	v_mfma_f32_16x16x32_bf16 v[48:51], v[188:191], v[196:199], v[48:51]
	v_mfma_f32_16x16x32_bf16 v[36:39], v[180:183], v[208:211], v[36:39]
	v_mfma_f32_16x16x32_bf16 v[32:35], v[188:191], v[208:211], v[32:35]
	v_mfma_f32_16x16x32_bf16 v[20:23], v[180:183], v[216:219], v[20:23]
	v_mfma_f32_16x16x32_bf16 v[16:19], v[188:191], v[216:219], v[16:19]
	v_mfma_f32_16x16x32_bf16 v[4:7], v[180:183], v[224:227], v[4:7]
	v_mfma_f32_16x16x32_bf16 v[0:3], v[188:191], v[224:227], v[0:3]
	s_setprio 0
	s_barrier
	s_add_i32 s67, 0, 0x18000
	v_add_u32_e32 v137, s67, v171
	s_add_i32 s68, 0, 0x1c000
	ds_read_b128 v[148:151], v137
	ds_read_b128 v[152:155], v137 offset:1024
	ds_read_b128 v[156:159], v137 offset:2048
	ds_read_b128 v[160:163], v137 offset:3072
	v_add_u32_e32 v137, s68, v171
	ds_read_b128 v[164:167], v137
	ds_read_b128 v[180:183], v137 offset:1024
	ds_read_b128 v[184:187], v137 offset:2048
	ds_read_b128 v[188:191], v137 offset:3072
	s_add_u32 s54, s54, 0x40000
	s_addc_u32 s55, s55, 0
	s_mov_b32 m0, s39
	v_lshl_add_u64 v[232:233], s[54:55], 0, v[128:129]
	ds_read_b128 v[192:195], v175 offset:32768
	ds_read_b128 v[196:199], v175 offset:33792
	ds_read_b128 v[204:207], v175 offset:34816
	ds_read_b128 v[208:211], v175 offset:35840
	ds_read_b128 v[212:215], v175 offset:36864
	ds_read_b128 v[216:219], v175 offset:37888
	ds_read_b128 v[220:223], v175 offset:38912
	ds_read_b128 v[224:227], v175 offset:39936
	global_load_lds_dwordx4 v[232:233], off
	v_lshl_add_u64 v[232:233], s[54:55], 0, v[132:133]
	s_mov_b32 m0, s41
	s_nop 0
	global_load_lds_dwordx4 v[232:233], off
	s_waitcnt vmcnt(8)
	s_waitcnt lgkmcnt(0)
	s_barrier
	s_setprio 1
	s_waitcnt lgkmcnt(0)
	v_mfma_f32_16x16x32_bf16 v[124:127], v[148:151], v[192:195], v[124:127]
	v_mfma_f32_16x16x32_bf16 v[120:123], v[156:159], v[192:195], v[120:123]
	v_mfma_f32_16x16x32_bf16 v[108:111], v[148:151], v[204:207], v[108:111]
	v_mfma_f32_16x16x32_bf16 v[104:107], v[156:159], v[204:207], v[104:107]
	v_mfma_f32_16x16x32_bf16 v[92:95], v[148:151], v[212:215], v[92:95]
	v_mfma_f32_16x16x32_bf16 v[88:91], v[156:159], v[212:215], v[88:91]
	v_mfma_f32_16x16x32_bf16 v[76:79], v[148:151], v[220:223], v[76:79]
	v_mfma_f32_16x16x32_bf16 v[72:75], v[156:159], v[220:223], v[72:75]
	v_mfma_f32_16x16x32_bf16 v[124:127], v[152:155], v[196:199], v[124:127]
	v_mfma_f32_16x16x32_bf16 v[120:123], v[160:163], v[196:199], v[120:123]
	v_mfma_f32_16x16x32_bf16 v[108:111], v[152:155], v[208:211], v[108:111]
	v_mfma_f32_16x16x32_bf16 v[104:107], v[160:163], v[208:211], v[104:107]
	v_mfma_f32_16x16x32_bf16 v[92:95], v[152:155], v[216:219], v[92:95]
	v_mfma_f32_16x16x32_bf16 v[88:91], v[160:163], v[216:219], v[88:91]
	v_mfma_f32_16x16x32_bf16 v[76:79], v[152:155], v[224:227], v[76:79]
	v_mfma_f32_16x16x32_bf16 v[72:75], v[160:163], v[224:227], v[72:75]
	s_setprio 0
	s_setprio 1
	v_mfma_f32_16x16x32_bf16 v[116:119], v[164:167], v[192:195], v[116:119]
	v_mfma_f32_16x16x32_bf16 v[112:115], v[184:187], v[192:195], v[112:115]
	v_mfma_f32_16x16x32_bf16 v[100:103], v[164:167], v[204:207], v[100:103]
	v_mfma_f32_16x16x32_bf16 v[96:99], v[184:187], v[204:207], v[96:99]
	v_mfma_f32_16x16x32_bf16 v[84:87], v[164:167], v[212:215], v[84:87]
	v_mfma_f32_16x16x32_bf16 v[80:83], v[184:187], v[212:215], v[80:83]
	v_mfma_f32_16x16x32_bf16 v[68:71], v[164:167], v[220:223], v[68:71]
	v_mfma_f32_16x16x32_bf16 v[64:67], v[184:187], v[220:223], v[64:67]
	v_mfma_f32_16x16x32_bf16 v[116:119], v[180:183], v[196:199], v[116:119]
	v_mfma_f32_16x16x32_bf16 v[112:115], v[188:191], v[196:199], v[112:115]
	v_mfma_f32_16x16x32_bf16 v[100:103], v[180:183], v[208:211], v[100:103]
	v_mfma_f32_16x16x32_bf16 v[96:99], v[188:191], v[208:211], v[96:99]
	v_mfma_f32_16x16x32_bf16 v[84:87], v[180:183], v[216:219], v[84:87]
	v_mfma_f32_16x16x32_bf16 v[80:83], v[188:191], v[216:219], v[80:83]
	v_mfma_f32_16x16x32_bf16 v[68:71], v[180:183], v[224:227], v[68:71]
	v_mfma_f32_16x16x32_bf16 v[64:67], v[188:191], v[224:227], v[64:67]
	s_setprio 0
	s_barrier
	s_add_i32 s54, s67, s31
	v_lshl_add_u64 v[168:169], v[168:169], 0, s[22:23]
	s_mov_b32 m0, s54
	ds_read_b128 v[192:195], v175 offset:49152
	ds_read_b128 v[196:199], v175 offset:50176
	ds_read_b128 v[204:207], v175 offset:51200
	ds_read_b128 v[208:211], v175 offset:52224
	ds_read_b128 v[212:215], v175 offset:53248
	ds_read_b128 v[216:219], v175 offset:54272
	ds_read_b128 v[220:223], v175 offset:55296
	ds_read_b128 v[224:227], v175 offset:56320
	global_load_lds_dwordx4 v[168:169], off
	s_add_i32 m0, s54, 0x2000
	s_add_u32 s52, s52, 0x40080
	v_lshl_add_u64 v[168:169], v[200:201], 0, s[22:23]
	s_addc_u32 s53, s53, 0
	s_add_i32 s54, s68, s31
	global_load_lds_dwordx4 v[168:169], off
	v_lshl_add_u64 v[168:169], s[52:53], 0, v[130:131]
	s_mov_b32 m0, s54
	s_nop 0
	global_load_lds_dwordx4 v[168:169], off
	v_lshl_add_u64 v[168:169], s[52:53], 0, v[134:135]
	s_add_i32 m0, s54, 0x2000
	s_nop 0
	global_load_lds_dwordx4 v[168:169], off
	v_lshl_add_u64 v[168:169], v[228:229], 0, s[22:23]
	s_mov_b32 m0, s60
	s_nop 0
	global_load_lds_dwordx4 v[168:169], off
	v_lshl_add_u64 v[168:169], v[230:231], 0, s[22:23]
	s_mov_b32 m0, s61
	s_nop 0
	global_load_lds_dwordx4 v[168:169], off
	s_waitcnt vmcnt(8)
	s_waitcnt lgkmcnt(0)
	s_barrier
	s_setprio 1
	s_waitcnt lgkmcnt(0)
	v_mfma_f32_16x16x32_bf16 v[60:63], v[148:151], v[192:195], v[60:63]
	v_mfma_f32_16x16x32_bf16 v[56:59], v[156:159], v[192:195], v[56:59]
	v_mfma_f32_16x16x32_bf16 v[44:47], v[148:151], v[204:207], v[44:47]
	v_mfma_f32_16x16x32_bf16 v[40:43], v[156:159], v[204:207], v[40:43]
	v_mfma_f32_16x16x32_bf16 v[28:31], v[148:151], v[212:215], v[28:31]
	v_mfma_f32_16x16x32_bf16 v[24:27], v[156:159], v[212:215], v[24:27]
	v_mfma_f32_16x16x32_bf16 v[12:15], v[148:151], v[220:223], v[12:15]
	v_mfma_f32_16x16x32_bf16 v[8:11], v[156:159], v[220:223], v[8:11]
	v_mfma_f32_16x16x32_bf16 v[60:63], v[152:155], v[196:199], v[60:63]
	v_mfma_f32_16x16x32_bf16 v[56:59], v[160:163], v[196:199], v[56:59]
	v_mfma_f32_16x16x32_bf16 v[44:47], v[152:155], v[208:211], v[44:47]
	v_mfma_f32_16x16x32_bf16 v[40:43], v[160:163], v[208:211], v[40:43]
	v_mfma_f32_16x16x32_bf16 v[28:31], v[152:155], v[216:219], v[28:31]
	v_mfma_f32_16x16x32_bf16 v[24:27], v[160:163], v[216:219], v[24:27]
	v_mfma_f32_16x16x32_bf16 v[12:15], v[152:155], v[224:227], v[12:15]
	v_mfma_f32_16x16x32_bf16 v[8:11], v[160:163], v[224:227], v[8:11]
	s_setprio 0
	s_setprio 1
	v_mfma_f32_16x16x32_bf16 v[52:55], v[164:167], v[192:195], v[52:55]
	v_mfma_f32_16x16x32_bf16 v[48:51], v[184:187], v[192:195], v[48:51]
	v_mfma_f32_16x16x32_bf16 v[36:39], v[164:167], v[204:207], v[36:39]
	v_mfma_f32_16x16x32_bf16 v[32:35], v[184:187], v[204:207], v[32:35]
	v_mfma_f32_16x16x32_bf16 v[20:23], v[164:167], v[212:215], v[20:23]
	v_mfma_f32_16x16x32_bf16 v[16:19], v[184:187], v[212:215], v[16:19]
	v_mfma_f32_16x16x32_bf16 v[4:7], v[164:167], v[220:223], v[4:7]
	v_mfma_f32_16x16x32_bf16 v[0:3], v[184:187], v[220:223], v[0:3]
	v_mfma_f32_16x16x32_bf16 v[52:55], v[180:183], v[196:199], v[52:55]
	v_mfma_f32_16x16x32_bf16 v[48:51], v[188:191], v[196:199], v[48:51]
	v_mfma_f32_16x16x32_bf16 v[36:39], v[180:183], v[208:211], v[36:39]
	v_mfma_f32_16x16x32_bf16 v[32:35], v[188:191], v[208:211], v[32:35]
	v_mfma_f32_16x16x32_bf16 v[20:23], v[180:183], v[216:219], v[20:23]
	v_mfma_f32_16x16x32_bf16 v[16:19], v[188:191], v[216:219], v[16:19]
	v_mfma_f32_16x16x32_bf16 v[4:7], v[180:183], v[224:227], v[4:7]
	v_mfma_f32_16x16x32_bf16 v[0:3], v[188:191], v[224:227], v[0:3]
	s_setprio 0
	s_add_i32 s66, s66, 2
	s_add_u32 s50, s50, 0x100
	s_addc_u32 s51, s51, 0
	s_add_u32 s43, s43, 0x100
	s_addc_u32 s45, s45, 0
	s_cmp_gt_u32 s66, 13
	s_barrier
	s_cbranch_scc0 .LBB0_220
	s_and_b64 vcc, exec, s[24:25]
	s_cbranch_vccz .LBB0_223
	s_barrier

.LBB0_401:
	ds_read_b128 v[128:131], v189
	ds_read_b128 v[132:135], v189 offset:1024
	ds_read_b128 v[136:139], v189 offset:2048
	ds_read_b128 v[140:143], v189 offset:3072
	ds_read_b128 v[144:147], v190
	ds_read_b128 v[148:151], v190 offset:1024
	ds_read_b128 v[168:171], v190 offset:2048
	ds_read_b128 v[172:175], v190 offset:3072
	s_add_u32 s4, s42, 0xfff80080
	s_addc_u32 s5, s43, -1
	s_cmp_eq_u32 s59, 28
	s_cselect_b32 s45, s35, s5
	s_cselect_b32 s44, s41, s4
	s_cselect_b32 s5, s31, s58
	s_cselect_b32 s4, s56, s57
	v_lshl_add_u64 v[184:185], s[42:43], 0, v[160:161]
	s_add_i32 m0, s47, 0xc000
	ds_read_b128 v[176:179], v191
	ds_read_b128 v[180:183], v191 offset:1024
	ds_read_b128 v[194:197], v191 offset:2048
	ds_read_b128 v[198:201], v191 offset:3072
	ds_read_b128 v[204:207], v191 offset:4096
	ds_read_b128 v[208:211], v191 offset:5120
	ds_read_b128 v[212:215], v191 offset:6144
	ds_read_b128 v[216:219], v191 offset:7168
	global_load_lds_dwordx4 v[184:185], off
	v_lshl_add_u64 v[184:185], s[42:43], 0, v[162:163]
	s_add_i32 m0, s47, 0xe000
	s_nop 0
	global_load_lds_dwordx4 v[184:185], off
	s_waitcnt vmcnt(8)
	s_waitcnt lgkmcnt(0)
	s_barrier
	s_setprio 1
	s_waitcnt lgkmcnt(0)
	v_mfma_f32_16x16x32_bf16 v[124:127], v[128:131], v[176:179], v[124:127]
	v_mfma_f32_16x16x32_bf16 v[120:123], v[136:139], v[176:179], v[120:123]
	v_mfma_f32_16x16x32_bf16 v[108:111], v[128:131], v[194:197], v[108:111]
	v_mfma_f32_16x16x32_bf16 v[104:107], v[136:139], v[194:197], v[104:107]
	v_mfma_f32_16x16x32_bf16 v[92:95], v[128:131], v[204:207], v[92:95]
	v_mfma_f32_16x16x32_bf16 v[88:91], v[136:139], v[204:207], v[88:91]
	v_mfma_f32_16x16x32_bf16 v[76:79], v[128:131], v[212:215], v[76:79]
	v_mfma_f32_16x16x32_bf16 v[72:75], v[136:139], v[212:215], v[72:75]
	v_mfma_f32_16x16x32_bf16 v[124:127], v[132:135], v[180:183], v[124:127]
	v_mfma_f32_16x16x32_bf16 v[120:123], v[140:143], v[180:183], v[120:123]
	v_mfma_f32_16x16x32_bf16 v[108:111], v[132:135], v[198:201], v[108:111]
	v_mfma_f32_16x16x32_bf16 v[104:107], v[140:143], v[198:201], v[104:107]
	v_mfma_f32_16x16x32_bf16 v[92:95], v[132:135], v[208:211], v[92:95]
	v_mfma_f32_16x16x32_bf16 v[88:91], v[140:143], v[208:211], v[88:91]
	v_mfma_f32_16x16x32_bf16 v[76:79], v[132:135], v[216:219], v[76:79]
	v_mfma_f32_16x16x32_bf16 v[72:75], v[140:143], v[216:219], v[72:75]
	s_setprio 0
	s_setprio 1
	v_mfma_f32_16x16x32_bf16 v[116:119], v[144:147], v[176:179], v[116:119]
	v_mfma_f32_16x16x32_bf16 v[112:115], v[168:171], v[176:179], v[112:115]
	v_mfma_f32_16x16x32_bf16 v[100:103], v[144:147], v[194:197], v[100:103]
	v_mfma_f32_16x16x32_bf16 v[96:99], v[168:171], v[194:197], v[96:99]
	v_mfma_f32_16x16x32_bf16 v[84:87], v[144:147], v[204:207], v[84:87]
	v_mfma_f32_16x16x32_bf16 v[80:83], v[168:171], v[204:207], v[80:83]
	v_mfma_f32_16x16x32_bf16 v[68:71], v[144:147], v[212:215], v[68:71]
	v_mfma_f32_16x16x32_bf16 v[64:67], v[168:171], v[212:215], v[64:67]
	v_mfma_f32_16x16x32_bf16 v[116:119], v[148:151], v[180:183], v[116:119]
	v_mfma_f32_16x16x32_bf16 v[112:115], v[172:175], v[180:183], v[112:115]
	v_mfma_f32_16x16x32_bf16 v[100:103], v[148:151], v[198:201], v[100:103]
	v_mfma_f32_16x16x32_bf16 v[96:99], v[172:175], v[198:201], v[96:99]
	v_mfma_f32_16x16x32_bf16 v[84:87], v[148:151], v[208:211], v[84:87]
	v_mfma_f32_16x16x32_bf16 v[80:83], v[172:175], v[208:211], v[80:83]
	v_mfma_f32_16x16x32_bf16 v[68:71], v[148:151], v[216:219], v[68:71]
	v_mfma_f32_16x16x32_bf16 v[64:67], v[172:175], v[216:219], v[64:67]
	s_setprio 0
	s_barrier
	s_add_i32 s60, s53, s46
	v_lshl_add_u64 v[184:185], s[4:5], 0, v[154:155]
	s_mov_b32 m0, s60
	ds_read_b128 v[176:179], v191 offset:16384
	ds_read_b128 v[180:183], v191 offset:17408
	ds_read_b128 v[194:197], v191 offset:18432
	ds_read_b128 v[198:201], v191 offset:19456
	ds_read_b128 v[204:207], v191 offset:20480
	ds_read_b128 v[208:211], v191 offset:21504
	ds_read_b128 v[212:215], v191 offset:22528
	ds_read_b128 v[216:219], v191 offset:23552
	global_load_lds_dwordx4 v[184:185], off
	s_add_i32 m0, s60, 0x2000
	s_add_u32 s60, s4, 0x80000
	v_lshl_add_u64 v[220:221], s[4:5], 0, v[158:159]
	s_addc_u32 s61, s5, 0
	s_add_i32 s62, s54, s46
	global_load_lds_dwordx4 v[220:221], off
	v_lshl_add_u64 v[222:223], s[60:61], 0, v[154:155]
	s_mov_b32 m0, s62
	v_lshl_add_u64 v[224:225], s[44:45], 0, v[156:157]
	global_load_lds_dwordx4 v[222:223], off
	v_lshl_add_u64 v[222:223], s[60:61], 0, v[158:159]
	s_add_i32 m0, s62, 0x2000
	s_nop 0
	global_load_lds_dwordx4 v[222:223], off
	v_lshl_add_u64 v[222:223], s[44:45], 0, v[152:153]
	s_mov_b32 m0, s47
	s_nop 0
	global_load_lds_dwordx4 v[222:223], off
	s_mov_b32 m0, s48
	s_nop 0
	global_load_lds_dwordx4 v[224:225], off
	s_waitcnt vmcnt(8)
	s_waitcnt lgkmcnt(0)
	s_barrier
	s_setprio 1
	s_waitcnt lgkmcnt(0)
	v_mfma_f32_16x16x32_bf16 v[60:63], v[128:131], v[176:179], v[60:63]
	v_mfma_f32_16x16x32_bf16 v[56:59], v[136:139], v[176:179], v[56:59]
	v_mfma_f32_16x16x32_bf16 v[44:47], v[128:131], v[194:197], v[44:47]
	v_mfma_f32_16x16x32_bf16 v[40:43], v[136:139], v[194:197], v[40:43]
	v_mfma_f32_16x16x32_bf16 v[28:31], v[128:131], v[204:207], v[28:31]
	v_mfma_f32_16x16x32_bf16 v[24:27], v[136:139], v[204:207], v[24:27]
	v_mfma_f32_16x16x32_bf16 v[12:15], v[128:131], v[212:215], v[12:15]
	v_mfma_f32_16x16x32_bf16 v[8:11], v[136:139], v[212:215], v[8:11]
	v_mfma_f32_16x16x32_bf16 v[60:63], v[132:135], v[180:183], v[60:63]
	v_mfma_f32_16x16x32_bf16 v[56:59], v[140:143], v[180:183], v[56:59]
	v_mfma_f32_16x16x32_bf16 v[44:47], v[132:135], v[198:201], v[44:47]
	v_mfma_f32_16x16x32_bf16 v[40:43], v[140:143], v[198:201], v[40:43]
	v_mfma_f32_16x16x32_bf16 v[28:31], v[132:135], v[208:211], v[28:31]
	v_mfma_f32_16x16x32_bf16 v[24:27], v[140:143], v[208:211], v[24:27]
	v_mfma_f32_16x16x32_bf16 v[12:15], v[132:135], v[216:219], v[12:15]
	v_mfma_f32_16x16x32_bf16 v[8:11], v[140:143], v[216:219], v[8:11]
	s_setprio 0
	s_setprio 1
	v_mfma_f32_16x16x32_bf16 v[52:55], v[144:147], v[176:179], v[52:55]
	v_mfma_f32_16x16x32_bf16 v[48:51], v[168:171], v[176:179], v[48:51]
	v_mfma_f32_16x16x32_bf16 v[36:39], v[144:147], v[194:197], v[36:39]
	v_mfma_f32_16x16x32_bf16 v[32:35], v[168:171], v[194:197], v[32:35]
	v_mfma_f32_16x16x32_bf16 v[20:23], v[144:147], v[204:207], v[20:23]
	v_mfma_f32_16x16x32_bf16 v[16:19], v[168:171], v[204:207], v[16:19]
	v_mfma_f32_16x16x32_bf16 v[4:7], v[144:147], v[212:215], v[4:7]
	v_mfma_f32_16x16x32_bf16 v[0:3], v[168:171], v[212:215], v[0:3]
	v_mfma_f32_16x16x32_bf16 v[52:55], v[148:151], v[180:183], v[52:55]
	v_mfma_f32_16x16x32_bf16 v[48:51], v[172:175], v[180:183], v[48:51]
	v_mfma_f32_16x16x32_bf16 v[36:39], v[148:151], v[198:201], v[36:39]
	v_mfma_f32_16x16x32_bf16 v[32:35], v[172:175], v[198:201], v[32:35]
	v_mfma_f32_16x16x32_bf16 v[20:23], v[148:151], v[208:211], v[20:23]
	v_mfma_f32_16x16x32_bf16 v[16:19], v[172:175], v[208:211], v[16:19]
	v_mfma_f32_16x16x32_bf16 v[4:7], v[148:151], v[216:219], v[4:7]
	v_mfma_f32_16x16x32_bf16 v[0:3], v[172:175], v[216:219], v[0:3]
	s_setprio 0
	s_barrier
	s_add_i32 s60, 0, 0x18000
	s_add_i32 s61, 0, 0x1c000
	v_add_u32_e32 v140, s60, v187
	v_add_u32_e32 v172, s61, v187
	ds_read_b128 v[128:131], v140
	ds_read_b128 v[132:135], v140 offset:1024
	ds_read_b128 v[136:139], v140 offset:2048
	ds_read_b128 v[140:143], v140 offset:3072
	ds_read_b128 v[144:147], v172
	ds_read_b128 v[148:151], v172 offset:1024
	ds_read_b128 v[168:171], v172 offset:2048
	ds_read_b128 v[172:175], v172 offset:3072
	s_add_u32 s44, s44, 0x80000
	s_addc_u32 s45, s45, 0
	s_mov_b32 m0, s49
	v_lshl_add_u64 v[226:227], s[44:45], 0, v[152:153]
	ds_read_b128 v[176:179], v191 offset:32768
	ds_read_b128 v[180:183], v191 offset:33792
	ds_read_b128 v[194:197], v191 offset:34816
	ds_read_b128 v[198:201], v191 offset:35840
	ds_read_b128 v[204:207], v191 offset:36864
	ds_read_b128 v[208:211], v191 offset:37888
	ds_read_b128 v[212:215], v191 offset:38912
	ds_read_b128 v[216:219], v191 offset:39936
	global_load_lds_dwordx4 v[226:227], off
	v_lshl_add_u64 v[226:227], s[44:45], 0, v[156:157]
	s_mov_b32 m0, s50
	s_nop 0
	global_load_lds_dwordx4 v[226:227], off
	s_waitcnt vmcnt(8)
	s_waitcnt lgkmcnt(0)
	s_barrier
	s_setprio 1
	s_waitcnt lgkmcnt(0)
	v_mfma_f32_16x16x32_bf16 v[124:127], v[128:131], v[176:179], v[124:127]
	v_mfma_f32_16x16x32_bf16 v[120:123], v[136:139], v[176:179], v[120:123]
	v_mfma_f32_16x16x32_bf16 v[108:111], v[128:131], v[194:197], v[108:111]
	v_mfma_f32_16x16x32_bf16 v[104:107], v[136:139], v[194:197], v[104:107]
	v_mfma_f32_16x16x32_bf16 v[92:95], v[128:131], v[204:207], v[92:95]
	v_mfma_f32_16x16x32_bf16 v[88:91], v[136:139], v[204:207], v[88:91]
	v_mfma_f32_16x16x32_bf16 v[76:79], v[128:131], v[212:215], v[76:79]
	v_mfma_f32_16x16x32_bf16 v[72:75], v[136:139], v[212:215], v[72:75]
	v_mfma_f32_16x16x32_bf16 v[124:127], v[132:135], v[180:183], v[124:127]
	v_mfma_f32_16x16x32_bf16 v[120:123], v[140:143], v[180:183], v[120:123]
	v_mfma_f32_16x16x32_bf16 v[108:111], v[132:135], v[198:201], v[108:111]
	v_mfma_f32_16x16x32_bf16 v[104:107], v[140:143], v[198:201], v[104:107]
	v_mfma_f32_16x16x32_bf16 v[92:95], v[132:135], v[208:211], v[92:95]
	v_mfma_f32_16x16x32_bf16 v[88:91], v[140:143], v[208:211], v[88:91]
	v_mfma_f32_16x16x32_bf16 v[76:79], v[132:135], v[216:219], v[76:79]
	v_mfma_f32_16x16x32_bf16 v[72:75], v[140:143], v[216:219], v[72:75]
	s_setprio 0
	s_setprio 1
	v_mfma_f32_16x16x32_bf16 v[116:119], v[144:147], v[176:179], v[116:119]
	v_mfma_f32_16x16x32_bf16 v[112:115], v[168:171], v[176:179], v[112:115]
	v_mfma_f32_16x16x32_bf16 v[100:103], v[144:147], v[194:197], v[100:103]
	v_mfma_f32_16x16x32_bf16 v[96:99], v[168:171], v[194:197], v[96:99]
	v_mfma_f32_16x16x32_bf16 v[84:87], v[144:147], v[204:207], v[84:87]
	v_mfma_f32_16x16x32_bf16 v[80:83], v[168:171], v[204:207], v[80:83]
	v_mfma_f32_16x16x32_bf16 v[68:71], v[144:147], v[212:215], v[68:71]
	v_mfma_f32_16x16x32_bf16 v[64:67], v[168:171], v[212:215], v[64:67]
	v_mfma_f32_16x16x32_bf16 v[116:119], v[148:151], v[180:183], v[116:119]
	v_mfma_f32_16x16x32_bf16 v[112:115], v[172:175], v[180:183], v[112:115]
	v_mfma_f32_16x16x32_bf16 v[100:103], v[148:151], v[198:201], v[100:103]
	v_mfma_f32_16x16x32_bf16 v[96:99], v[172:175], v[198:201], v[96:99]
	v_mfma_f32_16x16x32_bf16 v[84:87], v[148:151], v[208:211], v[84:87]
	v_mfma_f32_16x16x32_bf16 v[80:83], v[172:175], v[208:211], v[80:83]
	v_mfma_f32_16x16x32_bf16 v[68:71], v[148:151], v[216:219], v[68:71]
	v_mfma_f32_16x16x32_bf16 v[64:67], v[172:175], v[216:219], v[64:67]
	s_setprio 0
	s_barrier
	s_add_i32 s44, s60, s46
	v_lshl_add_u64 v[184:185], v[184:185], 0, s[26:27]
	s_mov_b32 m0, s44
	ds_read_b128 v[176:179], v191 offset:49152
	ds_read_b128 v[180:183], v191 offset:50176
	ds_read_b128 v[194:197], v191 offset:51200
	ds_read_b128 v[198:201], v191 offset:52224
	ds_read_b128 v[204:207], v191 offset:53248
	ds_read_b128 v[208:211], v191 offset:54272
	ds_read_b128 v[212:215], v191 offset:55296
	ds_read_b128 v[216:219], v191 offset:56320
	global_load_lds_dwordx4 v[184:185], off
	s_add_i32 m0, s44, 0x2000
	s_add_u32 s4, s4, 0x80080
	v_lshl_add_u64 v[184:185], v[220:221], 0, s[26:27]
	s_addc_u32 s5, s5, 0
	s_add_i32 s44, s61, s46
	global_load_lds_dwordx4 v[184:185], off
	v_lshl_add_u64 v[184:185], s[4:5], 0, v[154:155]
	s_mov_b32 m0, s44
	s_nop 0
	global_load_lds_dwordx4 v[184:185], off
	v_lshl_add_u64 v[184:185], s[4:5], 0, v[158:159]
	s_add_i32 m0, s44, 0x2000
	s_nop 0
	global_load_lds_dwordx4 v[184:185], off
	v_lshl_add_u64 v[184:185], v[222:223], 0, s[26:27]
	s_mov_b32 m0, s33
	s_nop 0
	global_load_lds_dwordx4 v[184:185], off
	v_lshl_add_u64 v[184:185], v[224:225], 0, s[26:27]
	s_mov_b32 m0, s52
	s_nop 0
	global_load_lds_dwordx4 v[184:185], off
	s_waitcnt vmcnt(8)
	s_waitcnt lgkmcnt(0)
	s_barrier
	s_setprio 1
	s_waitcnt lgkmcnt(0)
	v_mfma_f32_16x16x32_bf16 v[60:63], v[128:131], v[176:179], v[60:63]
	v_mfma_f32_16x16x32_bf16 v[56:59], v[136:139], v[176:179], v[56:59]
	v_mfma_f32_16x16x32_bf16 v[44:47], v[128:131], v[194:197], v[44:47]
	v_mfma_f32_16x16x32_bf16 v[40:43], v[136:139], v[194:197], v[40:43]
	v_mfma_f32_16x16x32_bf16 v[28:31], v[128:131], v[204:207], v[28:31]
	v_mfma_f32_16x16x32_bf16 v[24:27], v[136:139], v[204:207], v[24:27]
	v_mfma_f32_16x16x32_bf16 v[12:15], v[128:131], v[212:215], v[12:15]
	v_mfma_f32_16x16x32_bf16 v[8:11], v[136:139], v[212:215], v[8:11]
	v_mfma_f32_16x16x32_bf16 v[60:63], v[132:135], v[180:183], v[60:63]
	v_mfma_f32_16x16x32_bf16 v[56:59], v[140:143], v[180:183], v[56:59]
	v_mfma_f32_16x16x32_bf16 v[44:47], v[132:135], v[198:201], v[44:47]
	v_mfma_f32_16x16x32_bf16 v[40:43], v[140:143], v[198:201], v[40:43]
	v_mfma_f32_16x16x32_bf16 v[28:31], v[132:135], v[208:211], v[28:31]
	v_mfma_f32_16x16x32_bf16 v[24:27], v[140:143], v[208:211], v[24:27]
	v_mfma_f32_16x16x32_bf16 v[12:15], v[132:135], v[216:219], v[12:15]
	v_mfma_f32_16x16x32_bf16 v[8:11], v[140:143], v[216:219], v[8:11]
	s_setprio 0
	s_setprio 1
	v_mfma_f32_16x16x32_bf16 v[52:55], v[144:147], v[176:179], v[52:55]
	v_mfma_f32_16x16x32_bf16 v[48:51], v[168:171], v[176:179], v[48:51]
	v_mfma_f32_16x16x32_bf16 v[36:39], v[144:147], v[194:197], v[36:39]
	v_mfma_f32_16x16x32_bf16 v[32:35], v[168:171], v[194:197], v[32:35]
	v_mfma_f32_16x16x32_bf16 v[20:23], v[144:147], v[204:207], v[20:23]
	v_mfma_f32_16x16x32_bf16 v[16:19], v[168:171], v[204:207], v[16:19]
	v_mfma_f32_16x16x32_bf16 v[4:7], v[144:147], v[212:215], v[4:7]
	v_mfma_f32_16x16x32_bf16 v[0:3], v[168:171], v[212:215], v[0:3]
	v_mfma_f32_16x16x32_bf16 v[52:55], v[148:151], v[180:183], v[52:55]
	v_mfma_f32_16x16x32_bf16 v[48:51], v[172:175], v[180:183], v[48:51]
	v_mfma_f32_16x16x32_bf16 v[36:39], v[148:151], v[198:201], v[36:39]
	v_mfma_f32_16x16x32_bf16 v[32:35], v[172:175], v[198:201], v[32:35]
	v_mfma_f32_16x16x32_bf16 v[20:23], v[148:151], v[208:211], v[20:23]
	v_mfma_f32_16x16x32_bf16 v[16:19], v[172:175], v[208:211], v[16:19]
	v_mfma_f32_16x16x32_bf16 v[4:7], v[148:151], v[216:219], v[4:7]
	v_mfma_f32_16x16x32_bf16 v[0:3], v[172:175], v[216:219], v[0:3]
	s_setprio 0
	s_add_i32 s59, s59, 2
	s_add_u32 s42, s42, 0x100
	s_addc_u32 s43, s43, 0
	s_add_u32 s57, s57, 0x100
	s_addc_u32 s58, s58, 0
	s_cmp_gt_u32 s59, 29
	s_barrier
	s_cbranch_scc0 .LBB0_401
	s_and_b64 vcc, exec, s[28:29]
	s_cbranch_vccz .LBB0_404
	s_barrier

.LBB0_483:
	ds_read_b128 v[146:149], v169
	ds_read_b128 v[150:153], v169 offset:1024
	ds_read_b128 v[154:157], v169 offset:2048
	ds_read_b128 v[160:163], v169 offset:3072
	ds_read_b128 v[180:183], v171
	ds_read_b128 v[184:187], v171 offset:1024
	ds_read_b128 v[188:191], v171 offset:2048
	ds_read_b128 v[192:195], v171 offset:3072
	s_add_u32 s4, s10, 0xfffc0080
	s_addc_u32 s5, s11, -1
	s_cmp_eq_u32 s56, 12
	s_cselect_b32 s13, s9, s5
	s_cselect_b32 s12, s37, s4
	s_cselect_b32 s5, s35, s55
	s_cselect_b32 s4, s53, s54
	v_lshl_add_u64 v[200:201], s[10:11], 0, v[138:139]
	s_add_i32 m0, s42, 0xc000
	ds_read_b128 v[196:199], v173
	ds_read_b128 v[204:207], v173 offset:1024
	ds_read_b128 v[208:211], v173 offset:2048
	ds_read_b128 v[212:215], v173 offset:3072
	ds_read_b128 v[216:219], v173 offset:4096
	ds_read_b128 v[220:223], v173 offset:5120
	ds_read_b128 v[224:227], v173 offset:6144
	ds_read_b128 v[228:231], v173 offset:7168
	global_load_lds_dwordx4 v[200:201], off
	v_lshl_add_u64 v[200:201], s[10:11], 0, v[140:141]
	s_add_i32 m0, s42, 0xe000
	s_nop 0
	global_load_lds_dwordx4 v[200:201], off
	s_waitcnt vmcnt(8)
	s_waitcnt lgkmcnt(0)
	s_barrier
	s_setprio 1
	s_waitcnt lgkmcnt(0)
	v_mfma_f32_16x16x32_bf16 v[124:127], v[146:149], v[196:199], v[124:127]
	v_mfma_f32_16x16x32_bf16 v[116:119], v[154:157], v[196:199], v[116:119]
	v_mfma_f32_16x16x32_bf16 v[108:111], v[146:149], v[208:211], v[108:111]
	v_mfma_f32_16x16x32_bf16 v[100:103], v[154:157], v[208:211], v[100:103]
	v_mfma_f32_16x16x32_bf16 v[92:95], v[146:149], v[216:219], v[92:95]
	v_mfma_f32_16x16x32_bf16 v[84:87], v[154:157], v[216:219], v[84:87]
	v_mfma_f32_16x16x32_bf16 v[76:79], v[146:149], v[224:227], v[76:79]
	v_mfma_f32_16x16x32_bf16 v[68:71], v[154:157], v[224:227], v[68:71]
	v_mfma_f32_16x16x32_bf16 v[124:127], v[150:153], v[204:207], v[124:127]
	v_mfma_f32_16x16x32_bf16 v[116:119], v[160:163], v[204:207], v[116:119]
	v_mfma_f32_16x16x32_bf16 v[108:111], v[150:153], v[212:215], v[108:111]
	v_mfma_f32_16x16x32_bf16 v[100:103], v[160:163], v[212:215], v[100:103]
	v_mfma_f32_16x16x32_bf16 v[92:95], v[150:153], v[220:223], v[92:95]
	v_mfma_f32_16x16x32_bf16 v[84:87], v[160:163], v[220:223], v[84:87]
	v_mfma_f32_16x16x32_bf16 v[76:79], v[150:153], v[228:231], v[76:79]
	v_mfma_f32_16x16x32_bf16 v[68:71], v[160:163], v[228:231], v[68:71]
	s_setprio 0
	s_setprio 1
	v_mfma_f32_16x16x32_bf16 v[120:123], v[180:183], v[196:199], v[120:123]
	v_mfma_f32_16x16x32_bf16 v[112:115], v[188:191], v[196:199], v[112:115]
	v_mfma_f32_16x16x32_bf16 v[104:107], v[180:183], v[208:211], v[104:107]
	v_mfma_f32_16x16x32_bf16 v[96:99], v[188:191], v[208:211], v[96:99]
	v_mfma_f32_16x16x32_bf16 v[88:91], v[180:183], v[216:219], v[88:91]
	v_mfma_f32_16x16x32_bf16 v[80:83], v[188:191], v[216:219], v[80:83]
	v_mfma_f32_16x16x32_bf16 v[72:75], v[180:183], v[224:227], v[72:75]
	v_mfma_f32_16x16x32_bf16 v[64:67], v[188:191], v[224:227], v[64:67]
	v_mfma_f32_16x16x32_bf16 v[120:123], v[184:187], v[204:207], v[120:123]
	v_mfma_f32_16x16x32_bf16 v[112:115], v[192:195], v[204:207], v[112:115]
	v_mfma_f32_16x16x32_bf16 v[104:107], v[184:187], v[212:215], v[104:107]
	v_mfma_f32_16x16x32_bf16 v[96:99], v[192:195], v[212:215], v[96:99]
	v_mfma_f32_16x16x32_bf16 v[88:91], v[184:187], v[220:223], v[88:91]
	v_mfma_f32_16x16x32_bf16 v[80:83], v[192:195], v[220:223], v[80:83]
	v_mfma_f32_16x16x32_bf16 v[72:75], v[184:187], v[228:231], v[72:75]
	v_mfma_f32_16x16x32_bf16 v[64:67], v[192:195], v[228:231], v[64:67]
	s_setprio 0
	s_barrier
	s_add_i32 s57, s49, s23
	v_lshl_add_u64 v[200:201], s[4:5], 0, v[132:133]
	s_mov_b32 m0, s57
	ds_read_b128 v[196:199], v173 offset:16384
	ds_read_b128 v[204:207], v173 offset:17408
	ds_read_b128 v[208:211], v173 offset:18432
	ds_read_b128 v[212:215], v173 offset:19456
	ds_read_b128 v[216:219], v173 offset:20480
	ds_read_b128 v[220:223], v173 offset:21504
	ds_read_b128 v[224:227], v173 offset:22528
	ds_read_b128 v[228:231], v173 offset:23552
	global_load_lds_dwordx4 v[200:201], off
	s_add_i32 m0, s57, 0x2000
	s_add_u32 s58, s4, 0x40000
	v_lshl_add_u64 v[232:233], s[4:5], 0, v[128:129]
	s_addc_u32 s59, s5, 0
	s_add_i32 s57, s50, s23
	global_load_lds_dwordx4 v[232:233], off
	v_lshl_add_u64 v[234:235], s[58:59], 0, v[132:133]
	s_mov_b32 m0, s57
	v_lshl_add_u64 v[236:237], s[12:13], 0, v[130:131]
	global_load_lds_dwordx4 v[234:235], off
	v_lshl_add_u64 v[234:235], s[58:59], 0, v[128:129]
	s_add_i32 m0, s57, 0x2000
	s_nop 0
	global_load_lds_dwordx4 v[234:235], off
	v_lshl_add_u64 v[234:235], s[12:13], 0, v[134:135]
	s_mov_b32 m0, s42
	s_nop 0
	global_load_lds_dwordx4 v[234:235], off
	s_mov_b32 m0, s43
	s_nop 0
	global_load_lds_dwordx4 v[236:237], off
	s_waitcnt vmcnt(8)
	s_waitcnt lgkmcnt(0)
	s_barrier
	s_setprio 1
	s_waitcnt lgkmcnt(0)
	v_mfma_f32_16x16x32_bf16 v[60:63], v[146:149], v[196:199], v[60:63]
	v_mfma_f32_16x16x32_bf16 v[52:55], v[154:157], v[196:199], v[52:55]
	v_mfma_f32_16x16x32_bf16 v[44:47], v[146:149], v[208:211], v[44:47]
	v_mfma_f32_16x16x32_bf16 v[36:39], v[154:157], v[208:211], v[36:39]
	v_mfma_f32_16x16x32_bf16 v[28:31], v[146:149], v[216:219], v[28:31]
	v_mfma_f32_16x16x32_bf16 v[20:23], v[154:157], v[216:219], v[20:23]
	v_mfma_f32_16x16x32_bf16 v[12:15], v[146:149], v[224:227], v[12:15]
	v_mfma_f32_16x16x32_bf16 v[4:7], v[154:157], v[224:227], v[4:7]
	v_mfma_f32_16x16x32_bf16 v[60:63], v[150:153], v[204:207], v[60:63]
	v_mfma_f32_16x16x32_bf16 v[52:55], v[160:163], v[204:207], v[52:55]
	v_mfma_f32_16x16x32_bf16 v[44:47], v[150:153], v[212:215], v[44:47]
	v_mfma_f32_16x16x32_bf16 v[36:39], v[160:163], v[212:215], v[36:39]
	v_mfma_f32_16x16x32_bf16 v[28:31], v[150:153], v[220:223], v[28:31]
	v_mfma_f32_16x16x32_bf16 v[20:23], v[160:163], v[220:223], v[20:23]
	v_mfma_f32_16x16x32_bf16 v[12:15], v[150:153], v[228:231], v[12:15]
	v_mfma_f32_16x16x32_bf16 v[4:7], v[160:163], v[228:231], v[4:7]
	s_setprio 0
	s_setprio 1
	v_mfma_f32_16x16x32_bf16 v[56:59], v[180:183], v[196:199], v[56:59]
	v_mfma_f32_16x16x32_bf16 v[48:51], v[188:191], v[196:199], v[48:51]
	v_mfma_f32_16x16x32_bf16 v[40:43], v[180:183], v[208:211], v[40:43]
	v_mfma_f32_16x16x32_bf16 v[32:35], v[188:191], v[208:211], v[32:35]
	v_mfma_f32_16x16x32_bf16 v[24:27], v[180:183], v[216:219], v[24:27]
	v_mfma_f32_16x16x32_bf16 v[16:19], v[188:191], v[216:219], v[16:19]
	v_mfma_f32_16x16x32_bf16 v[8:11], v[180:183], v[224:227], v[8:11]
	v_mfma_f32_16x16x32_bf16 v[0:3], v[188:191], v[224:227], v[0:3]
	v_mfma_f32_16x16x32_bf16 v[56:59], v[184:187], v[204:207], v[56:59]
	v_mfma_f32_16x16x32_bf16 v[48:51], v[192:195], v[204:207], v[48:51]
	v_mfma_f32_16x16x32_bf16 v[40:43], v[184:187], v[212:215], v[40:43]
	v_mfma_f32_16x16x32_bf16 v[32:35], v[192:195], v[212:215], v[32:35]
	v_mfma_f32_16x16x32_bf16 v[24:27], v[184:187], v[220:223], v[24:27]
	v_mfma_f32_16x16x32_bf16 v[16:19], v[192:195], v[220:223], v[16:19]
	v_mfma_f32_16x16x32_bf16 v[8:11], v[184:187], v[228:231], v[8:11]
	v_mfma_f32_16x16x32_bf16 v[0:3], v[192:195], v[228:231], v[0:3]
	s_setprio 0
	s_barrier
	s_add_i32 s57, 0, 0x18000
	v_add_u32_e32 v158, s57, v165
	s_add_i32 s58, 0, 0x1c000
	ds_read_b128 v[146:149], v158
	ds_read_b128 v[150:153], v158 offset:1024
	ds_read_b128 v[154:157], v158 offset:2048
	ds_read_b128 v[160:163], v158 offset:3072
	v_add_u32_e32 v158, s58, v165
	ds_read_b128 v[180:183], v158
	ds_read_b128 v[184:187], v158 offset:1024
	ds_read_b128 v[188:191], v158 offset:2048
	ds_read_b128 v[192:195], v158 offset:3072
	s_add_u32 s12, s12, 0x40000
	s_addc_u32 s13, s13, 0
	s_mov_b32 m0, s44
	v_lshl_add_u64 v[238:239], s[12:13], 0, v[134:135]
	ds_read_b128 v[196:199], v173 offset:32768
	ds_read_b128 v[204:207], v173 offset:33792
	ds_read_b128 v[208:211], v173 offset:34816
	ds_read_b128 v[212:215], v173 offset:35840
	ds_read_b128 v[216:219], v173 offset:36864
	ds_read_b128 v[220:223], v173 offset:37888
	ds_read_b128 v[224:227], v173 offset:38912
	ds_read_b128 v[228:231], v173 offset:39936
	global_load_lds_dwordx4 v[238:239], off
	v_lshl_add_u64 v[238:239], s[12:13], 0, v[130:131]
	s_mov_b32 m0, s45
	s_nop 0
	global_load_lds_dwordx4 v[238:239], off
	s_waitcnt vmcnt(8)
	s_waitcnt lgkmcnt(0)
	s_barrier
	s_setprio 1
	s_waitcnt lgkmcnt(0)
	v_mfma_f32_16x16x32_bf16 v[124:127], v[146:149], v[196:199], v[124:127]
	v_mfma_f32_16x16x32_bf16 v[116:119], v[154:157], v[196:199], v[116:119]
	v_mfma_f32_16x16x32_bf16 v[108:111], v[146:149], v[208:211], v[108:111]
	v_mfma_f32_16x16x32_bf16 v[100:103], v[154:157], v[208:211], v[100:103]
	v_mfma_f32_16x16x32_bf16 v[92:95], v[146:149], v[216:219], v[92:95]
	v_mfma_f32_16x16x32_bf16 v[84:87], v[154:157], v[216:219], v[84:87]
	v_mfma_f32_16x16x32_bf16 v[76:79], v[146:149], v[224:227], v[76:79]
	v_mfma_f32_16x16x32_bf16 v[68:71], v[154:157], v[224:227], v[68:71]
	v_mfma_f32_16x16x32_bf16 v[124:127], v[150:153], v[204:207], v[124:127]
	v_mfma_f32_16x16x32_bf16 v[116:119], v[160:163], v[204:207], v[116:119]
	v_mfma_f32_16x16x32_bf16 v[108:111], v[150:153], v[212:215], v[108:111]
	v_mfma_f32_16x16x32_bf16 v[100:103], v[160:163], v[212:215], v[100:103]
	v_mfma_f32_16x16x32_bf16 v[92:95], v[150:153], v[220:223], v[92:95]
	v_mfma_f32_16x16x32_bf16 v[84:87], v[160:163], v[220:223], v[84:87]
	v_mfma_f32_16x16x32_bf16 v[76:79], v[150:153], v[228:231], v[76:79]
	v_mfma_f32_16x16x32_bf16 v[68:71], v[160:163], v[228:231], v[68:71]
	s_setprio 0
	s_setprio 1
	v_mfma_f32_16x16x32_bf16 v[120:123], v[180:183], v[196:199], v[120:123]
	v_mfma_f32_16x16x32_bf16 v[112:115], v[188:191], v[196:199], v[112:115]
	v_mfma_f32_16x16x32_bf16 v[104:107], v[180:183], v[208:211], v[104:107]
	v_mfma_f32_16x16x32_bf16 v[96:99], v[188:191], v[208:211], v[96:99]
	v_mfma_f32_16x16x32_bf16 v[88:91], v[180:183], v[216:219], v[88:91]
	v_mfma_f32_16x16x32_bf16 v[80:83], v[188:191], v[216:219], v[80:83]
	v_mfma_f32_16x16x32_bf16 v[72:75], v[180:183], v[224:227], v[72:75]
	v_mfma_f32_16x16x32_bf16 v[64:67], v[188:191], v[224:227], v[64:67]
	v_mfma_f32_16x16x32_bf16 v[120:123], v[184:187], v[204:207], v[120:123]
	v_mfma_f32_16x16x32_bf16 v[112:115], v[192:195], v[204:207], v[112:115]
	v_mfma_f32_16x16x32_bf16 v[104:107], v[184:187], v[212:215], v[104:107]
	v_mfma_f32_16x16x32_bf16 v[96:99], v[192:195], v[212:215], v[96:99]
	v_mfma_f32_16x16x32_bf16 v[88:91], v[184:187], v[220:223], v[88:91]
	v_mfma_f32_16x16x32_bf16 v[80:83], v[192:195], v[220:223], v[80:83]
	v_mfma_f32_16x16x32_bf16 v[72:75], v[184:187], v[228:231], v[72:75]
	v_mfma_f32_16x16x32_bf16 v[64:67], v[192:195], v[228:231], v[64:67]
	s_setprio 0
	s_barrier
	s_add_i32 s12, s57, s23
	v_lshl_add_u64 v[200:201], v[200:201], 0, s[28:29]
	s_mov_b32 m0, s12
	ds_read_b128 v[196:199], v173 offset:49152
	ds_read_b128 v[204:207], v173 offset:50176
	ds_read_b128 v[208:211], v173 offset:51200
	ds_read_b128 v[212:215], v173 offset:52224
	ds_read_b128 v[216:219], v173 offset:53248
	ds_read_b128 v[220:223], v173 offset:54272
	ds_read_b128 v[224:227], v173 offset:55296
	ds_read_b128 v[228:231], v173 offset:56320
	global_load_lds_dwordx4 v[200:201], off
	s_add_i32 m0, s12, 0x2000
	s_add_u32 s4, s4, 0x40080
	v_lshl_add_u64 v[200:201], v[232:233], 0, s[28:29]
	s_addc_u32 s5, s5, 0
	s_add_i32 s12, s58, s23
	global_load_lds_dwordx4 v[200:201], off
	v_lshl_add_u64 v[200:201], s[4:5], 0, v[132:133]
	s_mov_b32 m0, s12
	s_nop 0
	global_load_lds_dwordx4 v[200:201], off
	v_lshl_add_u64 v[200:201], s[4:5], 0, v[128:129]
	s_add_i32 m0, s12, 0x2000
	s_nop 0
	global_load_lds_dwordx4 v[200:201], off
	v_lshl_add_u64 v[200:201], v[234:235], 0, s[28:29]
	s_mov_b32 m0, s47
	s_nop 0
	global_load_lds_dwordx4 v[200:201], off
	v_lshl_add_u64 v[200:201], v[236:237], 0, s[28:29]
	s_mov_b32 m0, s48
	s_nop 0
	global_load_lds_dwordx4 v[200:201], off
	s_waitcnt vmcnt(8)
	s_waitcnt lgkmcnt(0)
	s_barrier
	s_setprio 1
	s_waitcnt lgkmcnt(0)
	v_mfma_f32_16x16x32_bf16 v[60:63], v[146:149], v[196:199], v[60:63]
	v_mfma_f32_16x16x32_bf16 v[52:55], v[154:157], v[196:199], v[52:55]
	v_mfma_f32_16x16x32_bf16 v[44:47], v[146:149], v[208:211], v[44:47]
	v_mfma_f32_16x16x32_bf16 v[36:39], v[154:157], v[208:211], v[36:39]
	v_mfma_f32_16x16x32_bf16 v[28:31], v[146:149], v[216:219], v[28:31]
	v_mfma_f32_16x16x32_bf16 v[20:23], v[154:157], v[216:219], v[20:23]
	v_mfma_f32_16x16x32_bf16 v[12:15], v[146:149], v[224:227], v[12:15]
	v_mfma_f32_16x16x32_bf16 v[4:7], v[154:157], v[224:227], v[4:7]
	v_mfma_f32_16x16x32_bf16 v[60:63], v[150:153], v[204:207], v[60:63]
	v_mfma_f32_16x16x32_bf16 v[52:55], v[160:163], v[204:207], v[52:55]
	v_mfma_f32_16x16x32_bf16 v[44:47], v[150:153], v[212:215], v[44:47]
	v_mfma_f32_16x16x32_bf16 v[36:39], v[160:163], v[212:215], v[36:39]
	v_mfma_f32_16x16x32_bf16 v[28:31], v[150:153], v[220:223], v[28:31]
	v_mfma_f32_16x16x32_bf16 v[20:23], v[160:163], v[220:223], v[20:23]
	v_mfma_f32_16x16x32_bf16 v[12:15], v[150:153], v[228:231], v[12:15]
	v_mfma_f32_16x16x32_bf16 v[4:7], v[160:163], v[228:231], v[4:7]
	s_setprio 0
	s_setprio 1
	v_mfma_f32_16x16x32_bf16 v[56:59], v[180:183], v[196:199], v[56:59]
	v_mfma_f32_16x16x32_bf16 v[48:51], v[188:191], v[196:199], v[48:51]
	v_mfma_f32_16x16x32_bf16 v[40:43], v[180:183], v[208:211], v[40:43]
	v_mfma_f32_16x16x32_bf16 v[32:35], v[188:191], v[208:211], v[32:35]
	v_mfma_f32_16x16x32_bf16 v[24:27], v[180:183], v[216:219], v[24:27]
	v_mfma_f32_16x16x32_bf16 v[16:19], v[188:191], v[216:219], v[16:19]
	v_mfma_f32_16x16x32_bf16 v[8:11], v[180:183], v[224:227], v[8:11]
	v_mfma_f32_16x16x32_bf16 v[0:3], v[188:191], v[224:227], v[0:3]
	v_mfma_f32_16x16x32_bf16 v[56:59], v[184:187], v[204:207], v[56:59]
	v_mfma_f32_16x16x32_bf16 v[48:51], v[192:195], v[204:207], v[48:51]
	v_mfma_f32_16x16x32_bf16 v[40:43], v[184:187], v[212:215], v[40:43]
	v_mfma_f32_16x16x32_bf16 v[32:35], v[192:195], v[212:215], v[32:35]
	v_mfma_f32_16x16x32_bf16 v[24:27], v[184:187], v[220:223], v[24:27]
	v_mfma_f32_16x16x32_bf16 v[16:19], v[192:195], v[220:223], v[16:19]
	v_mfma_f32_16x16x32_bf16 v[8:11], v[184:187], v[228:231], v[8:11]
	v_mfma_f32_16x16x32_bf16 v[0:3], v[192:195], v[228:231], v[0:3]
	s_setprio 0
	s_add_i32 s56, s56, 2
	s_add_u32 s10, s10, 0x100
	s_addc_u32 s11, s11, 0
	s_add_u32 s54, s54, 0x100
	s_addc_u32 s55, s55, 0
	s_cmp_gt_u32 s56, 13
	s_barrier
	s_cbranch_scc0 .LBB0_483
	s_and_b64 vcc, exec, s[30:31]
	s_cbranch_vccz .LBB0_486
	s_barrier

.LBB0_559:
	ds_read_b128 v[128:131], v189
	ds_read_b128 v[132:135], v189 offset:1024
	ds_read_b128 v[136:139], v189 offset:2048
	ds_read_b128 v[140:143], v189 offset:3072
	ds_read_b128 v[144:147], v190
	ds_read_b128 v[148:151], v190 offset:1024
	ds_read_b128 v[168:171], v190 offset:2048
	ds_read_b128 v[172:175], v190 offset:3072
	s_add_u32 s4, s22, 0x100
	s_addc_u32 s5, s23, 0
	s_cmp_eq_u32 s57, 40
	s_cselect_b32 s41, s11, s5
	s_cselect_b32 s40, s10, s4
	s_cselect_b32 s39, s37, s56
	s_cselect_b32 s38, s36, s55
	v_lshl_add_u64 v[184:185], s[22:23], 0, v[160:161]
	s_add_i32 m0, s43, 0xc000
	ds_read_b128 v[176:179], v191
	ds_read_b128 v[180:183], v191 offset:1024
	ds_read_b128 v[194:197], v191 offset:2048
	ds_read_b128 v[198:201], v191 offset:3072
	ds_read_b128 v[204:207], v191 offset:4096
	ds_read_b128 v[208:211], v191 offset:5120
	ds_read_b128 v[212:215], v191 offset:6144
	ds_read_b128 v[216:219], v191 offset:7168
	global_load_lds_dwordx4 v[184:185], off
	v_lshl_add_u64 v[184:185], s[22:23], 0, v[162:163]
	s_add_i32 m0, s43, 0xe000
	s_nop 0
	global_load_lds_dwordx4 v[184:185], off
	s_waitcnt vmcnt(8)
	s_waitcnt lgkmcnt(0)
	s_barrier
	s_setprio 1
	s_waitcnt lgkmcnt(0)
	v_mfma_f32_16x16x32_bf16 v[124:127], v[128:131], v[176:179], v[124:127]
	v_mfma_f32_16x16x32_bf16 v[120:123], v[136:139], v[176:179], v[120:123]
	v_mfma_f32_16x16x32_bf16 v[108:111], v[128:131], v[194:197], v[108:111]
	v_mfma_f32_16x16x32_bf16 v[104:107], v[136:139], v[194:197], v[104:107]
	v_mfma_f32_16x16x32_bf16 v[92:95], v[128:131], v[204:207], v[92:95]
	v_mfma_f32_16x16x32_bf16 v[88:91], v[136:139], v[204:207], v[88:91]
	v_mfma_f32_16x16x32_bf16 v[76:79], v[128:131], v[212:215], v[76:79]
	v_mfma_f32_16x16x32_bf16 v[72:75], v[136:139], v[212:215], v[72:75]
	v_mfma_f32_16x16x32_bf16 v[124:127], v[132:135], v[180:183], v[124:127]
	v_mfma_f32_16x16x32_bf16 v[120:123], v[140:143], v[180:183], v[120:123]
	v_mfma_f32_16x16x32_bf16 v[108:111], v[132:135], v[198:201], v[108:111]
	v_mfma_f32_16x16x32_bf16 v[104:107], v[140:143], v[198:201], v[104:107]
	v_mfma_f32_16x16x32_bf16 v[92:95], v[132:135], v[208:211], v[92:95]
	v_mfma_f32_16x16x32_bf16 v[88:91], v[140:143], v[208:211], v[88:91]
	v_mfma_f32_16x16x32_bf16 v[76:79], v[132:135], v[216:219], v[76:79]
	v_mfma_f32_16x16x32_bf16 v[72:75], v[140:143], v[216:219], v[72:75]
	s_setprio 0
	s_setprio 1
	v_mfma_f32_16x16x32_bf16 v[116:119], v[144:147], v[176:179], v[116:119]
	v_mfma_f32_16x16x32_bf16 v[112:115], v[168:171], v[176:179], v[112:115]
	v_mfma_f32_16x16x32_bf16 v[100:103], v[144:147], v[194:197], v[100:103]
	v_mfma_f32_16x16x32_bf16 v[96:99], v[168:171], v[194:197], v[96:99]
	v_mfma_f32_16x16x32_bf16 v[84:87], v[144:147], v[204:207], v[84:87]
	v_mfma_f32_16x16x32_bf16 v[80:83], v[168:171], v[204:207], v[80:83]
	v_mfma_f32_16x16x32_bf16 v[68:71], v[144:147], v[212:215], v[68:71]
	v_mfma_f32_16x16x32_bf16 v[64:67], v[168:171], v[212:215], v[64:67]
	v_mfma_f32_16x16x32_bf16 v[116:119], v[148:151], v[180:183], v[116:119]
	v_mfma_f32_16x16x32_bf16 v[112:115], v[172:175], v[180:183], v[112:115]
	v_mfma_f32_16x16x32_bf16 v[100:103], v[148:151], v[198:201], v[100:103]
	v_mfma_f32_16x16x32_bf16 v[96:99], v[172:175], v[198:201], v[96:99]
	v_mfma_f32_16x16x32_bf16 v[84:87], v[148:151], v[208:211], v[84:87]
	v_mfma_f32_16x16x32_bf16 v[80:83], v[172:175], v[208:211], v[80:83]
	v_mfma_f32_16x16x32_bf16 v[68:71], v[148:151], v[216:219], v[68:71]
	v_mfma_f32_16x16x32_bf16 v[64:67], v[172:175], v[216:219], v[64:67]
	s_setprio 0
	s_barrier
	s_add_i32 s22, s49, s42
	v_lshl_add_u64 v[184:185], s[38:39], 0, v[154:155]
	s_mov_b32 m0, s22
	ds_read_b128 v[176:179], v191 offset:16384
	ds_read_b128 v[180:183], v191 offset:17408
	ds_read_b128 v[194:197], v191 offset:18432
	ds_read_b128 v[198:201], v191 offset:19456
	ds_read_b128 v[204:207], v191 offset:20480
	ds_read_b128 v[208:211], v191 offset:21504
	ds_read_b128 v[212:215], v191 offset:22528
	ds_read_b128 v[216:219], v191 offset:23552
	global_load_lds_dwordx4 v[184:185], off
	s_add_i32 m0, s22, 0x2000
	s_add_u32 s22, s38, 0xb0000
	v_lshl_add_u64 v[220:221], s[38:39], 0, v[158:159]
	s_addc_u32 s23, s39, 0
	s_add_i32 s58, s50, s42
	global_load_lds_dwordx4 v[220:221], off
	v_lshl_add_u64 v[222:223], s[22:23], 0, v[154:155]
	s_mov_b32 m0, s58
	v_lshl_add_u64 v[224:225], s[40:41], 0, v[156:157]
	global_load_lds_dwordx4 v[222:223], off
	v_lshl_add_u64 v[222:223], s[22:23], 0, v[158:159]
	s_add_i32 m0, s58, 0x2000
	s_nop 0
	global_load_lds_dwordx4 v[222:223], off
	v_lshl_add_u64 v[222:223], s[40:41], 0, v[152:153]
	s_mov_b32 m0, s43
	s_nop 0
	global_load_lds_dwordx4 v[222:223], off
	s_mov_b32 m0, s44
	s_nop 0
	global_load_lds_dwordx4 v[224:225], off
	s_waitcnt vmcnt(8)
	s_waitcnt lgkmcnt(0)
	s_barrier
	s_setprio 1
	s_waitcnt lgkmcnt(0)
	v_mfma_f32_16x16x32_bf16 v[60:63], v[128:131], v[176:179], v[60:63]
	v_mfma_f32_16x16x32_bf16 v[56:59], v[136:139], v[176:179], v[56:59]
	v_mfma_f32_16x16x32_bf16 v[44:47], v[128:131], v[194:197], v[44:47]
	v_mfma_f32_16x16x32_bf16 v[40:43], v[136:139], v[194:197], v[40:43]
	v_mfma_f32_16x16x32_bf16 v[28:31], v[128:131], v[204:207], v[28:31]
	v_mfma_f32_16x16x32_bf16 v[24:27], v[136:139], v[204:207], v[24:27]
	v_mfma_f32_16x16x32_bf16 v[12:15], v[128:131], v[212:215], v[12:15]
	v_mfma_f32_16x16x32_bf16 v[8:11], v[136:139], v[212:215], v[8:11]
	v_mfma_f32_16x16x32_bf16 v[60:63], v[132:135], v[180:183], v[60:63]
	v_mfma_f32_16x16x32_bf16 v[56:59], v[140:143], v[180:183], v[56:59]
	v_mfma_f32_16x16x32_bf16 v[44:47], v[132:135], v[198:201], v[44:47]
	v_mfma_f32_16x16x32_bf16 v[40:43], v[140:143], v[198:201], v[40:43]
	v_mfma_f32_16x16x32_bf16 v[28:31], v[132:135], v[208:211], v[28:31]
	v_mfma_f32_16x16x32_bf16 v[24:27], v[140:143], v[208:211], v[24:27]
	v_mfma_f32_16x16x32_bf16 v[12:15], v[132:135], v[216:219], v[12:15]
	v_mfma_f32_16x16x32_bf16 v[8:11], v[140:143], v[216:219], v[8:11]
	s_setprio 0
	s_setprio 1
	v_mfma_f32_16x16x32_bf16 v[52:55], v[144:147], v[176:179], v[52:55]
	v_mfma_f32_16x16x32_bf16 v[48:51], v[168:171], v[176:179], v[48:51]
	v_mfma_f32_16x16x32_bf16 v[36:39], v[144:147], v[194:197], v[36:39]
	v_mfma_f32_16x16x32_bf16 v[32:35], v[168:171], v[194:197], v[32:35]
	v_mfma_f32_16x16x32_bf16 v[20:23], v[144:147], v[204:207], v[20:23]
	v_mfma_f32_16x16x32_bf16 v[16:19], v[168:171], v[204:207], v[16:19]
	v_mfma_f32_16x16x32_bf16 v[4:7], v[144:147], v[212:215], v[4:7]
	v_mfma_f32_16x16x32_bf16 v[0:3], v[168:171], v[212:215], v[0:3]
	v_mfma_f32_16x16x32_bf16 v[52:55], v[148:151], v[180:183], v[52:55]
	v_mfma_f32_16x16x32_bf16 v[48:51], v[172:175], v[180:183], v[48:51]
	v_mfma_f32_16x16x32_bf16 v[36:39], v[148:151], v[198:201], v[36:39]
	v_mfma_f32_16x16x32_bf16 v[32:35], v[172:175], v[198:201], v[32:35]
	v_mfma_f32_16x16x32_bf16 v[20:23], v[148:151], v[208:211], v[20:23]
	v_mfma_f32_16x16x32_bf16 v[16:19], v[172:175], v[208:211], v[16:19]
	v_mfma_f32_16x16x32_bf16 v[4:7], v[148:151], v[216:219], v[4:7]
	v_mfma_f32_16x16x32_bf16 v[0:3], v[172:175], v[216:219], v[0:3]
	s_setprio 0
	s_barrier
	s_add_i32 s58, 0, 0x18000
	s_add_i32 s59, 0, 0x1c000
	v_add_u32_e32 v140, s58, v187
	v_add_u32_e32 v172, s59, v187
	ds_read_b128 v[128:131], v140
	ds_read_b128 v[132:135], v140 offset:1024
	ds_read_b128 v[136:139], v140 offset:2048
	ds_read_b128 v[140:143], v140 offset:3072
	ds_read_b128 v[144:147], v172
	ds_read_b128 v[148:151], v172 offset:1024
	ds_read_b128 v[168:171], v172 offset:2048
	ds_read_b128 v[172:175], v172 offset:3072
	s_add_u32 s22, s40, 0xb0000
	s_addc_u32 s23, s41, 0
	s_mov_b32 m0, s45
	v_lshl_add_u64 v[226:227], s[22:23], 0, v[152:153]
	ds_read_b128 v[176:179], v191 offset:32768
	ds_read_b128 v[180:183], v191 offset:33792
	ds_read_b128 v[194:197], v191 offset:34816
	ds_read_b128 v[198:201], v191 offset:35840
	ds_read_b128 v[204:207], v191 offset:36864
	ds_read_b128 v[208:211], v191 offset:37888
	ds_read_b128 v[212:215], v191 offset:38912
	ds_read_b128 v[216:219], v191 offset:39936
	global_load_lds_dwordx4 v[226:227], off
	v_lshl_add_u64 v[226:227], s[22:23], 0, v[156:157]
	s_mov_b32 m0, s46
	s_nop 0
	global_load_lds_dwordx4 v[226:227], off
	s_waitcnt vmcnt(8)
	s_waitcnt lgkmcnt(0)
	s_barrier
	s_setprio 1
	s_waitcnt lgkmcnt(0)
	v_mfma_f32_16x16x32_bf16 v[124:127], v[128:131], v[176:179], v[124:127]
	v_mfma_f32_16x16x32_bf16 v[120:123], v[136:139], v[176:179], v[120:123]
	v_mfma_f32_16x16x32_bf16 v[108:111], v[128:131], v[194:197], v[108:111]
	v_mfma_f32_16x16x32_bf16 v[104:107], v[136:139], v[194:197], v[104:107]
	v_mfma_f32_16x16x32_bf16 v[92:95], v[128:131], v[204:207], v[92:95]
	v_mfma_f32_16x16x32_bf16 v[88:91], v[136:139], v[204:207], v[88:91]
	v_mfma_f32_16x16x32_bf16 v[76:79], v[128:131], v[212:215], v[76:79]
	v_mfma_f32_16x16x32_bf16 v[72:75], v[136:139], v[212:215], v[72:75]
	v_mfma_f32_16x16x32_bf16 v[124:127], v[132:135], v[180:183], v[124:127]
	v_mfma_f32_16x16x32_bf16 v[120:123], v[140:143], v[180:183], v[120:123]
	v_mfma_f32_16x16x32_bf16 v[108:111], v[132:135], v[198:201], v[108:111]
	v_mfma_f32_16x16x32_bf16 v[104:107], v[140:143], v[198:201], v[104:107]
	v_mfma_f32_16x16x32_bf16 v[92:95], v[132:135], v[208:211], v[92:95]
	v_mfma_f32_16x16x32_bf16 v[88:91], v[140:143], v[208:211], v[88:91]
	v_mfma_f32_16x16x32_bf16 v[76:79], v[132:135], v[216:219], v[76:79]
	v_mfma_f32_16x16x32_bf16 v[72:75], v[140:143], v[216:219], v[72:75]
	s_setprio 0
	s_setprio 1
	v_mfma_f32_16x16x32_bf16 v[116:119], v[144:147], v[176:179], v[116:119]
	v_mfma_f32_16x16x32_bf16 v[112:115], v[168:171], v[176:179], v[112:115]
	v_mfma_f32_16x16x32_bf16 v[100:103], v[144:147], v[194:197], v[100:103]
	v_mfma_f32_16x16x32_bf16 v[96:99], v[168:171], v[194:197], v[96:99]
	v_mfma_f32_16x16x32_bf16 v[84:87], v[144:147], v[204:207], v[84:87]
	v_mfma_f32_16x16x32_bf16 v[80:83], v[168:171], v[204:207], v[80:83]
	v_mfma_f32_16x16x32_bf16 v[68:71], v[144:147], v[212:215], v[68:71]
	v_mfma_f32_16x16x32_bf16 v[64:67], v[168:171], v[212:215], v[64:67]
	v_mfma_f32_16x16x32_bf16 v[116:119], v[148:151], v[180:183], v[116:119]
	v_mfma_f32_16x16x32_bf16 v[112:115], v[172:175], v[180:183], v[112:115]
	v_mfma_f32_16x16x32_bf16 v[100:103], v[148:151], v[198:201], v[100:103]
	v_mfma_f32_16x16x32_bf16 v[96:99], v[172:175], v[198:201], v[96:99]
	v_mfma_f32_16x16x32_bf16 v[84:87], v[148:151], v[208:211], v[84:87]
	v_mfma_f32_16x16x32_bf16 v[80:83], v[172:175], v[208:211], v[80:83]
	v_mfma_f32_16x16x32_bf16 v[68:71], v[148:151], v[216:219], v[68:71]
	v_mfma_f32_16x16x32_bf16 v[64:67], v[172:175], v[216:219], v[64:67]
	s_setprio 0
	s_barrier
	s_add_i32 s22, s58, s42
	v_lshl_add_u64 v[184:185], v[184:185], 0, s[30:31]
	s_mov_b32 m0, s22
	ds_read_b128 v[176:179], v191 offset:49152
	ds_read_b128 v[180:183], v191 offset:50176
	ds_read_b128 v[194:197], v191 offset:51200
	ds_read_b128 v[198:201], v191 offset:52224
	ds_read_b128 v[204:207], v191 offset:53248
	ds_read_b128 v[208:211], v191 offset:54272
	ds_read_b128 v[212:215], v191 offset:55296
	ds_read_b128 v[216:219], v191 offset:56320
	global_load_lds_dwordx4 v[184:185], off
	s_add_i32 m0, s22, 0x2000
	s_add_u32 s22, s38, 0xb0080
	v_lshl_add_u64 v[184:185], v[220:221], 0, s[30:31]
	s_addc_u32 s23, s39, 0
	s_add_i32 s38, s59, s42
	global_load_lds_dwordx4 v[184:185], off
	v_lshl_add_u64 v[184:185], s[22:23], 0, v[154:155]
	s_mov_b32 m0, s38
	s_nop 0
	global_load_lds_dwordx4 v[184:185], off
	v_lshl_add_u64 v[184:185], s[22:23], 0, v[158:159]
	s_add_i32 m0, s38, 0x2000
	s_nop 0
	global_load_lds_dwordx4 v[184:185], off
	v_lshl_add_u64 v[184:185], v[222:223], 0, s[30:31]
	s_mov_b32 m0, s33
	s_nop 0
	global_load_lds_dwordx4 v[184:185], off
	v_lshl_add_u64 v[184:185], v[224:225], 0, s[30:31]
	s_mov_b32 m0, s48
	s_nop 0
	global_load_lds_dwordx4 v[184:185], off
	s_waitcnt vmcnt(8)
	s_waitcnt lgkmcnt(0)
	s_barrier
	s_setprio 1
	s_waitcnt lgkmcnt(0)
	v_mfma_f32_16x16x32_bf16 v[60:63], v[128:131], v[176:179], v[60:63]
	v_mfma_f32_16x16x32_bf16 v[56:59], v[136:139], v[176:179], v[56:59]
	v_mfma_f32_16x16x32_bf16 v[44:47], v[128:131], v[194:197], v[44:47]
	v_mfma_f32_16x16x32_bf16 v[40:43], v[136:139], v[194:197], v[40:43]
	v_mfma_f32_16x16x32_bf16 v[28:31], v[128:131], v[204:207], v[28:31]
	v_mfma_f32_16x16x32_bf16 v[24:27], v[136:139], v[204:207], v[24:27]
	v_mfma_f32_16x16x32_bf16 v[12:15], v[128:131], v[212:215], v[12:15]
	v_mfma_f32_16x16x32_bf16 v[8:11], v[136:139], v[212:215], v[8:11]
	v_mfma_f32_16x16x32_bf16 v[60:63], v[132:135], v[180:183], v[60:63]
	v_mfma_f32_16x16x32_bf16 v[56:59], v[140:143], v[180:183], v[56:59]
	v_mfma_f32_16x16x32_bf16 v[44:47], v[132:135], v[198:201], v[44:47]
	v_mfma_f32_16x16x32_bf16 v[40:43], v[140:143], v[198:201], v[40:43]
	v_mfma_f32_16x16x32_bf16 v[28:31], v[132:135], v[208:211], v[28:31]
	v_mfma_f32_16x16x32_bf16 v[24:27], v[140:143], v[208:211], v[24:27]
	v_mfma_f32_16x16x32_bf16 v[12:15], v[132:135], v[216:219], v[12:15]
	v_mfma_f32_16x16x32_bf16 v[8:11], v[140:143], v[216:219], v[8:11]
	s_setprio 0
	s_setprio 1
	v_mfma_f32_16x16x32_bf16 v[52:55], v[144:147], v[176:179], v[52:55]
	v_mfma_f32_16x16x32_bf16 v[48:51], v[168:171], v[176:179], v[48:51]
	v_mfma_f32_16x16x32_bf16 v[36:39], v[144:147], v[194:197], v[36:39]
	v_mfma_f32_16x16x32_bf16 v[32:35], v[168:171], v[194:197], v[32:35]
	v_mfma_f32_16x16x32_bf16 v[20:23], v[144:147], v[204:207], v[20:23]
	v_mfma_f32_16x16x32_bf16 v[16:19], v[168:171], v[204:207], v[16:19]
	v_mfma_f32_16x16x32_bf16 v[4:7], v[144:147], v[212:215], v[4:7]
	v_mfma_f32_16x16x32_bf16 v[0:3], v[168:171], v[212:215], v[0:3]
	v_mfma_f32_16x16x32_bf16 v[52:55], v[148:151], v[180:183], v[52:55]
	v_mfma_f32_16x16x32_bf16 v[48:51], v[172:175], v[180:183], v[48:51]
	v_mfma_f32_16x16x32_bf16 v[36:39], v[148:151], v[198:201], v[36:39]
	v_mfma_f32_16x16x32_bf16 v[32:35], v[172:175], v[198:201], v[32:35]
	v_mfma_f32_16x16x32_bf16 v[20:23], v[148:151], v[208:211], v[20:23]
	v_mfma_f32_16x16x32_bf16 v[16:19], v[172:175], v[208:211], v[16:19]
	v_mfma_f32_16x16x32_bf16 v[4:7], v[148:151], v[216:219], v[4:7]
	v_mfma_f32_16x16x32_bf16 v[0:3], v[172:175], v[216:219], v[0:3]
	s_setprio 0
	s_add_i32 s57, s57, 2
	s_add_u32 s55, s55, 0x100
	s_addc_u32 s56, s56, 0
	s_cmp_gt_u32 s57, 41
	s_mov_b64 s[22:23], s[4:5]
	s_barrier
	s_cbranch_scc0 .LBB0_559
	s_and_b64 vcc, exec, s[34:35]
	s_cbranch_vccz .LBB0_562
	s_barrier

.LBB0_643:
	ds_read_b128 v[128:131], v191
	ds_read_b128 v[132:135], v191 offset:1024
	ds_read_b128 v[156:159], v191 offset:2048
	ds_read_b128 v[160:163], v191 offset:3072
	ds_read_b128 v[164:167], v192
	ds_read_b128 v[168:171], v192 offset:1024
	ds_read_b128 v[172:175], v192 offset:2048
	ds_read_b128 v[176:179], v192 offset:3072
	s_add_u32 s4, s22, 0xfffc0080
	s_addc_u32 s5, s23, -1
	s_cmp_eq_u32 s63, 12
	s_cselect_b32 s47, s13, s5
	s_cselect_b32 s46, s17, s4
	s_cselect_b32 s5, s33, s62
	s_cselect_b32 s4, s39, s41
	v_lshl_add_u64 v[224:225], s[22:23], 0, v[148:149]
	s_add_i32 m0, s49, 0xc000
	ds_read_b128 v[180:183], v193
	ds_read_b128 v[184:187], v193 offset:1024
	ds_read_b128 v[198:201], v193 offset:2048
	ds_read_b128 v[204:207], v193 offset:3072
	ds_read_b128 v[208:211], v193 offset:4096
	ds_read_b128 v[212:215], v193 offset:5120
	ds_read_b128 v[216:219], v193 offset:6144
	ds_read_b128 v[220:223], v193 offset:7168
	global_load_lds_dwordx4 v[224:225], off
	v_lshl_add_u64 v[224:225], s[22:23], 0, v[150:151]
	s_add_i32 m0, s49, 0xe000
	s_nop 0
	global_load_lds_dwordx4 v[224:225], off
	s_waitcnt vmcnt(8)
	s_waitcnt lgkmcnt(0)
	s_barrier
	s_setprio 1
	s_waitcnt lgkmcnt(0)
	v_mfma_f32_16x16x32_bf16 v[124:127], v[128:131], v[180:183], v[124:127]
	v_mfma_f32_16x16x32_bf16 v[120:123], v[156:159], v[180:183], v[120:123]
	v_mfma_f32_16x16x32_bf16 v[108:111], v[128:131], v[198:201], v[108:111]
	v_mfma_f32_16x16x32_bf16 v[104:107], v[156:159], v[198:201], v[104:107]
	v_mfma_f32_16x16x32_bf16 v[92:95], v[128:131], v[208:211], v[92:95]
	v_mfma_f32_16x16x32_bf16 v[88:91], v[156:159], v[208:211], v[88:91]
	v_mfma_f32_16x16x32_bf16 v[76:79], v[128:131], v[216:219], v[76:79]
	v_mfma_f32_16x16x32_bf16 v[72:75], v[156:159], v[216:219], v[72:75]
	v_mfma_f32_16x16x32_bf16 v[124:127], v[132:135], v[184:187], v[124:127]
	v_mfma_f32_16x16x32_bf16 v[120:123], v[160:163], v[184:187], v[120:123]
	v_mfma_f32_16x16x32_bf16 v[108:111], v[132:135], v[204:207], v[108:111]
	v_mfma_f32_16x16x32_bf16 v[104:107], v[160:163], v[204:207], v[104:107]
	v_mfma_f32_16x16x32_bf16 v[92:95], v[132:135], v[212:215], v[92:95]
	v_mfma_f32_16x16x32_bf16 v[88:91], v[160:163], v[212:215], v[88:91]
	v_mfma_f32_16x16x32_bf16 v[76:79], v[132:135], v[220:223], v[76:79]
	v_mfma_f32_16x16x32_bf16 v[72:75], v[160:163], v[220:223], v[72:75]
	s_setprio 0
	s_setprio 1
	v_mfma_f32_16x16x32_bf16 v[116:119], v[164:167], v[180:183], v[116:119]
	v_mfma_f32_16x16x32_bf16 v[112:115], v[172:175], v[180:183], v[112:115]
	v_mfma_f32_16x16x32_bf16 v[100:103], v[164:167], v[198:201], v[100:103]
	v_mfma_f32_16x16x32_bf16 v[96:99], v[172:175], v[198:201], v[96:99]
	v_mfma_f32_16x16x32_bf16 v[84:87], v[164:167], v[208:211], v[84:87]
	v_mfma_f32_16x16x32_bf16 v[80:83], v[172:175], v[208:211], v[80:83]
	v_mfma_f32_16x16x32_bf16 v[68:71], v[164:167], v[216:219], v[68:71]
	v_mfma_f32_16x16x32_bf16 v[64:67], v[172:175], v[216:219], v[64:67]
	v_mfma_f32_16x16x32_bf16 v[116:119], v[168:171], v[184:187], v[116:119]
	v_mfma_f32_16x16x32_bf16 v[112:115], v[176:179], v[184:187], v[112:115]
	v_mfma_f32_16x16x32_bf16 v[100:103], v[168:171], v[204:207], v[100:103]
	v_mfma_f32_16x16x32_bf16 v[96:99], v[176:179], v[204:207], v[96:99]
	v_mfma_f32_16x16x32_bf16 v[84:87], v[168:171], v[212:215], v[84:87]
	v_mfma_f32_16x16x32_bf16 v[80:83], v[176:179], v[212:215], v[80:83]
	v_mfma_f32_16x16x32_bf16 v[68:71], v[168:171], v[220:223], v[68:71]
	v_mfma_f32_16x16x32_bf16 v[64:67], v[176:179], v[220:223], v[64:67]
	s_setprio 0
	s_barrier
	s_add_i32 s64, s59, s48
	v_lshl_add_u64 v[224:225], s[4:5], 0, v[138:139]
	s_mov_b32 m0, s64
	ds_read_b128 v[180:183], v193 offset:16384
	ds_read_b128 v[184:187], v193 offset:17408
	ds_read_b128 v[198:201], v193 offset:18432
	ds_read_b128 v[204:207], v193 offset:19456
	ds_read_b128 v[208:211], v193 offset:20480
	ds_read_b128 v[212:215], v193 offset:21504
	ds_read_b128 v[216:219], v193 offset:22528
	ds_read_b128 v[220:223], v193 offset:23552
	global_load_lds_dwordx4 v[224:225], off
	s_add_i32 m0, s64, 0x2000
	s_add_u32 s64, s4, 0x40000
	v_lshl_add_u64 v[226:227], s[4:5], 0, v[142:143]
	s_addc_u32 s65, s5, 0
	s_add_i32 s66, s60, s48
	global_load_lds_dwordx4 v[226:227], off
	v_lshl_add_u64 v[228:229], s[64:65], 0, v[138:139]
	s_mov_b32 m0, s66
	v_lshl_add_u64 v[230:231], s[46:47], 0, v[140:141]
	global_load_lds_dwordx4 v[228:229], off
	v_lshl_add_u64 v[228:229], s[64:65], 0, v[142:143]
	s_add_i32 m0, s66, 0x2000
	s_nop 0
	global_load_lds_dwordx4 v[228:229], off
	v_lshl_add_u64 v[228:229], s[46:47], 0, v[136:137]
	s_mov_b32 m0, s49
	s_nop 0
	global_load_lds_dwordx4 v[228:229], off
	s_mov_b32 m0, s50
	s_nop 0
	global_load_lds_dwordx4 v[230:231], off
	s_waitcnt vmcnt(8)
	s_waitcnt lgkmcnt(0)
	s_barrier
	s_setprio 1
	s_waitcnt lgkmcnt(0)
	v_mfma_f32_16x16x32_bf16 v[60:63], v[128:131], v[180:183], v[60:63]
	v_mfma_f32_16x16x32_bf16 v[56:59], v[156:159], v[180:183], v[56:59]
	v_mfma_f32_16x16x32_bf16 v[44:47], v[128:131], v[198:201], v[44:47]
	v_mfma_f32_16x16x32_bf16 v[40:43], v[156:159], v[198:201], v[40:43]
	v_mfma_f32_16x16x32_bf16 v[28:31], v[128:131], v[208:211], v[28:31]
	v_mfma_f32_16x16x32_bf16 v[24:27], v[156:159], v[208:211], v[24:27]
	v_mfma_f32_16x16x32_bf16 v[12:15], v[128:131], v[216:219], v[12:15]
	v_mfma_f32_16x16x32_bf16 v[8:11], v[156:159], v[216:219], v[8:11]
	v_mfma_f32_16x16x32_bf16 v[60:63], v[132:135], v[184:187], v[60:63]
	v_mfma_f32_16x16x32_bf16 v[56:59], v[160:163], v[184:187], v[56:59]
	v_mfma_f32_16x16x32_bf16 v[44:47], v[132:135], v[204:207], v[44:47]
	v_mfma_f32_16x16x32_bf16 v[40:43], v[160:163], v[204:207], v[40:43]
	v_mfma_f32_16x16x32_bf16 v[28:31], v[132:135], v[212:215], v[28:31]
	v_mfma_f32_16x16x32_bf16 v[24:27], v[160:163], v[212:215], v[24:27]
	v_mfma_f32_16x16x32_bf16 v[12:15], v[132:135], v[220:223], v[12:15]
	v_mfma_f32_16x16x32_bf16 v[8:11], v[160:163], v[220:223], v[8:11]
	s_setprio 0
	s_setprio 1
	v_mfma_f32_16x16x32_bf16 v[52:55], v[164:167], v[180:183], v[52:55]
	v_mfma_f32_16x16x32_bf16 v[48:51], v[172:175], v[180:183], v[48:51]
	v_mfma_f32_16x16x32_bf16 v[36:39], v[164:167], v[198:201], v[36:39]
	v_mfma_f32_16x16x32_bf16 v[32:35], v[172:175], v[198:201], v[32:35]
	v_mfma_f32_16x16x32_bf16 v[20:23], v[164:167], v[208:211], v[20:23]
	v_mfma_f32_16x16x32_bf16 v[16:19], v[172:175], v[208:211], v[16:19]
	v_mfma_f32_16x16x32_bf16 v[4:7], v[164:167], v[216:219], v[4:7]
	v_mfma_f32_16x16x32_bf16 v[0:3], v[172:175], v[216:219], v[0:3]
	v_mfma_f32_16x16x32_bf16 v[52:55], v[168:171], v[184:187], v[52:55]
	v_mfma_f32_16x16x32_bf16 v[48:51], v[176:179], v[184:187], v[48:51]
	v_mfma_f32_16x16x32_bf16 v[36:39], v[168:171], v[204:207], v[36:39]
	v_mfma_f32_16x16x32_bf16 v[32:35], v[176:179], v[204:207], v[32:35]
	v_mfma_f32_16x16x32_bf16 v[20:23], v[168:171], v[212:215], v[20:23]
	v_mfma_f32_16x16x32_bf16 v[16:19], v[176:179], v[212:215], v[16:19]
	v_mfma_f32_16x16x32_bf16 v[4:7], v[168:171], v[220:223], v[4:7]
	v_mfma_f32_16x16x32_bf16 v[0:3], v[176:179], v[220:223], v[0:3]
	s_setprio 0
	s_barrier
	s_add_i32 s64, 0, 0x18000
	v_add_u32_e32 v144, s64, v189
	s_add_i32 s65, 0, 0x1c000
	ds_read_b128 v[128:131], v144
	ds_read_b128 v[132:135], v144 offset:1024
	ds_read_b128 v[156:159], v144 offset:2048
	ds_read_b128 v[160:163], v144 offset:3072
	v_add_u32_e32 v144, s65, v189
	ds_read_b128 v[164:167], v144
	ds_read_b128 v[168:171], v144 offset:1024
	ds_read_b128 v[172:175], v144 offset:2048
	ds_read_b128 v[176:179], v144 offset:3072
	s_add_u32 s46, s46, 0x40000
	s_addc_u32 s47, s47, 0
	s_mov_b32 m0, s51
	v_lshl_add_u64 v[232:233], s[46:47], 0, v[136:137]
	ds_read_b128 v[180:183], v193 offset:32768
	ds_read_b128 v[184:187], v193 offset:33792
	ds_read_b128 v[198:201], v193 offset:34816
	ds_read_b128 v[204:207], v193 offset:35840
	ds_read_b128 v[208:211], v193 offset:36864
	ds_read_b128 v[212:215], v193 offset:37888
	ds_read_b128 v[216:219], v193 offset:38912
	ds_read_b128 v[220:223], v193 offset:39936
	global_load_lds_dwordx4 v[232:233], off
	v_lshl_add_u64 v[232:233], s[46:47], 0, v[140:141]
	s_mov_b32 m0, s52
	s_nop 0
	global_load_lds_dwordx4 v[232:233], off
	s_waitcnt vmcnt(8)
	s_waitcnt lgkmcnt(0)
	s_barrier
	s_setprio 1
	s_waitcnt lgkmcnt(0)
	v_mfma_f32_16x16x32_bf16 v[124:127], v[128:131], v[180:183], v[124:127]
	v_mfma_f32_16x16x32_bf16 v[120:123], v[156:159], v[180:183], v[120:123]
	v_mfma_f32_16x16x32_bf16 v[108:111], v[128:131], v[198:201], v[108:111]
	v_mfma_f32_16x16x32_bf16 v[104:107], v[156:159], v[198:201], v[104:107]
	v_mfma_f32_16x16x32_bf16 v[92:95], v[128:131], v[208:211], v[92:95]
	v_mfma_f32_16x16x32_bf16 v[88:91], v[156:159], v[208:211], v[88:91]
	v_mfma_f32_16x16x32_bf16 v[76:79], v[128:131], v[216:219], v[76:79]
	v_mfma_f32_16x16x32_bf16 v[72:75], v[156:159], v[216:219], v[72:75]
	v_mfma_f32_16x16x32_bf16 v[124:127], v[132:135], v[184:187], v[124:127]
	v_mfma_f32_16x16x32_bf16 v[120:123], v[160:163], v[184:187], v[120:123]
	v_mfma_f32_16x16x32_bf16 v[108:111], v[132:135], v[204:207], v[108:111]
	v_mfma_f32_16x16x32_bf16 v[104:107], v[160:163], v[204:207], v[104:107]
	v_mfma_f32_16x16x32_bf16 v[92:95], v[132:135], v[212:215], v[92:95]
	v_mfma_f32_16x16x32_bf16 v[88:91], v[160:163], v[212:215], v[88:91]
	v_mfma_f32_16x16x32_bf16 v[76:79], v[132:135], v[220:223], v[76:79]
	v_mfma_f32_16x16x32_bf16 v[72:75], v[160:163], v[220:223], v[72:75]
	s_setprio 0
	s_setprio 1
	v_mfma_f32_16x16x32_bf16 v[116:119], v[164:167], v[180:183], v[116:119]
	v_mfma_f32_16x16x32_bf16 v[112:115], v[172:175], v[180:183], v[112:115]
	v_mfma_f32_16x16x32_bf16 v[100:103], v[164:167], v[198:201], v[100:103]
	v_mfma_f32_16x16x32_bf16 v[96:99], v[172:175], v[198:201], v[96:99]
	v_mfma_f32_16x16x32_bf16 v[84:87], v[164:167], v[208:211], v[84:87]
	v_mfma_f32_16x16x32_bf16 v[80:83], v[172:175], v[208:211], v[80:83]
	v_mfma_f32_16x16x32_bf16 v[68:71], v[164:167], v[216:219], v[68:71]
	v_mfma_f32_16x16x32_bf16 v[64:67], v[172:175], v[216:219], v[64:67]
	v_mfma_f32_16x16x32_bf16 v[116:119], v[168:171], v[184:187], v[116:119]
	v_mfma_f32_16x16x32_bf16 v[112:115], v[176:179], v[184:187], v[112:115]
	v_mfma_f32_16x16x32_bf16 v[100:103], v[168:171], v[204:207], v[100:103]
	v_mfma_f32_16x16x32_bf16 v[96:99], v[176:179], v[204:207], v[96:99]
	v_mfma_f32_16x16x32_bf16 v[84:87], v[168:171], v[212:215], v[84:87]
	v_mfma_f32_16x16x32_bf16 v[80:83], v[176:179], v[212:215], v[80:83]
	v_mfma_f32_16x16x32_bf16 v[68:71], v[168:171], v[220:223], v[68:71]
	v_mfma_f32_16x16x32_bf16 v[64:67], v[176:179], v[220:223], v[64:67]
	s_setprio 0
	s_barrier
	s_add_i32 s46, s64, s48
	v_lshl_add_u64 v[224:225], v[224:225], 0, s[30:31]
	s_mov_b32 m0, s46
	ds_read_b128 v[180:183], v193 offset:49152
	ds_read_b128 v[184:187], v193 offset:50176
	ds_read_b128 v[198:201], v193 offset:51200
	ds_read_b128 v[204:207], v193 offset:52224
	ds_read_b128 v[208:211], v193 offset:53248
	ds_read_b128 v[212:215], v193 offset:54272
	ds_read_b128 v[216:219], v193 offset:55296
	ds_read_b128 v[220:223], v193 offset:56320
	global_load_lds_dwordx4 v[224:225], off
	s_add_i32 m0, s46, 0x2000
	s_add_u32 s4, s4, 0x40080
	v_lshl_add_u64 v[224:225], v[226:227], 0, s[30:31]
	s_addc_u32 s5, s5, 0
	s_add_i32 s46, s65, s48
	global_load_lds_dwordx4 v[224:225], off
	v_lshl_add_u64 v[224:225], s[4:5], 0, v[138:139]
	s_mov_b32 m0, s46
	s_nop 0
	global_load_lds_dwordx4 v[224:225], off
	v_lshl_add_u64 v[224:225], s[4:5], 0, v[142:143]
	s_add_i32 m0, s46, 0x2000
	s_nop 0
	global_load_lds_dwordx4 v[224:225], off
	v_lshl_add_u64 v[224:225], v[228:229], 0, s[30:31]
	s_mov_b32 m0, s56
	s_nop 0
	global_load_lds_dwordx4 v[224:225], off
	v_lshl_add_u64 v[224:225], v[230:231], 0, s[30:31]
	s_mov_b32 m0, s57
	s_nop 0
	global_load_lds_dwordx4 v[224:225], off
	s_waitcnt vmcnt(8)
	s_waitcnt lgkmcnt(0)
	s_barrier
	s_setprio 1
	s_waitcnt lgkmcnt(0)
	v_mfma_f32_16x16x32_bf16 v[60:63], v[128:131], v[180:183], v[60:63]
	v_mfma_f32_16x16x32_bf16 v[56:59], v[156:159], v[180:183], v[56:59]
	v_mfma_f32_16x16x32_bf16 v[44:47], v[128:131], v[198:201], v[44:47]
	v_mfma_f32_16x16x32_bf16 v[40:43], v[156:159], v[198:201], v[40:43]
	v_mfma_f32_16x16x32_bf16 v[28:31], v[128:131], v[208:211], v[28:31]
	v_mfma_f32_16x16x32_bf16 v[24:27], v[156:159], v[208:211], v[24:27]
	v_mfma_f32_16x16x32_bf16 v[12:15], v[128:131], v[216:219], v[12:15]
	v_mfma_f32_16x16x32_bf16 v[8:11], v[156:159], v[216:219], v[8:11]
	v_mfma_f32_16x16x32_bf16 v[60:63], v[132:135], v[184:187], v[60:63]
	v_mfma_f32_16x16x32_bf16 v[56:59], v[160:163], v[184:187], v[56:59]
	v_mfma_f32_16x16x32_bf16 v[44:47], v[132:135], v[204:207], v[44:47]
	v_mfma_f32_16x16x32_bf16 v[40:43], v[160:163], v[204:207], v[40:43]
	v_mfma_f32_16x16x32_bf16 v[28:31], v[132:135], v[212:215], v[28:31]
	v_mfma_f32_16x16x32_bf16 v[24:27], v[160:163], v[212:215], v[24:27]
	v_mfma_f32_16x16x32_bf16 v[12:15], v[132:135], v[220:223], v[12:15]
	v_mfma_f32_16x16x32_bf16 v[8:11], v[160:163], v[220:223], v[8:11]
	s_setprio 0
	s_setprio 1
	v_mfma_f32_16x16x32_bf16 v[52:55], v[164:167], v[180:183], v[52:55]
	v_mfma_f32_16x16x32_bf16 v[48:51], v[172:175], v[180:183], v[48:51]
	v_mfma_f32_16x16x32_bf16 v[36:39], v[164:167], v[198:201], v[36:39]
	v_mfma_f32_16x16x32_bf16 v[32:35], v[172:175], v[198:201], v[32:35]
	v_mfma_f32_16x16x32_bf16 v[20:23], v[164:167], v[208:211], v[20:23]
	v_mfma_f32_16x16x32_bf16 v[16:19], v[172:175], v[208:211], v[16:19]
	v_mfma_f32_16x16x32_bf16 v[4:7], v[164:167], v[216:219], v[4:7]
	v_mfma_f32_16x16x32_bf16 v[0:3], v[172:175], v[216:219], v[0:3]
	v_mfma_f32_16x16x32_bf16 v[52:55], v[168:171], v[184:187], v[52:55]
	v_mfma_f32_16x16x32_bf16 v[48:51], v[176:179], v[184:187], v[48:51]
	v_mfma_f32_16x16x32_bf16 v[36:39], v[168:171], v[204:207], v[36:39]
	v_mfma_f32_16x16x32_bf16 v[32:35], v[176:179], v[204:207], v[32:35]
	v_mfma_f32_16x16x32_bf16 v[20:23], v[168:171], v[212:215], v[20:23]
	v_mfma_f32_16x16x32_bf16 v[16:19], v[176:179], v[212:215], v[16:19]
	v_mfma_f32_16x16x32_bf16 v[4:7], v[168:171], v[220:223], v[4:7]
	v_mfma_f32_16x16x32_bf16 v[0:3], v[176:179], v[220:223], v[0:3]
	s_setprio 0
	s_add_i32 s63, s63, 2
	s_add_u32 s22, s22, 0x100
	s_addc_u32 s23, s23, 0
	s_add_u32 s41, s41, 0x100
	s_addc_u32 s62, s62, 0
	s_cmp_gt_u32 s63, 13
	s_barrier
	s_cbranch_scc0 .LBB0_643
	s_and_b64 vcc, exec, s[34:35]
	s_cbranch_vccz .LBB0_646
	s_barrier

.LBB0_966:
	ds_read_b128 v[128:131], v189
	ds_read_b128 v[132:135], v189 offset:1024
	ds_read_b128 v[136:139], v189 offset:2048
	ds_read_b128 v[140:143], v189 offset:3072
	ds_read_b128 v[144:147], v190
	ds_read_b128 v[148:151], v190 offset:1024
	ds_read_b128 v[168:171], v190 offset:2048
	ds_read_b128 v[172:175], v190 offset:3072
	s_add_u32 s4, s22, 0xfffc0080
	s_addc_u32 s5, s23, -1
	s_cmp_eq_u32 s58, 12
	s_cselect_b32 s43, s35, s5
	s_cselect_b32 s42, s41, s4
	s_cselect_b32 s5, s31, s57
	s_cselect_b32 s4, s55, s56
	v_lshl_add_u64 v[184:185], s[22:23], 0, v[160:161]
	s_add_i32 m0, s46, 0xc000
	ds_read_b128 v[176:179], v191
	ds_read_b128 v[180:183], v191 offset:1024
	ds_read_b128 v[192:195], v191 offset:2048
	ds_read_b128 v[198:201], v191 offset:3072
	ds_read_b128 v[204:207], v191 offset:4096
	ds_read_b128 v[208:211], v191 offset:5120
	ds_read_b128 v[212:215], v191 offset:6144
	ds_read_b128 v[216:219], v191 offset:7168
	global_load_lds_dwordx4 v[184:185], off
	v_lshl_add_u64 v[184:185], s[22:23], 0, v[162:163]
	s_add_i32 m0, s46, 0xe000
	s_nop 0
	global_load_lds_dwordx4 v[184:185], off
	s_waitcnt vmcnt(8)
	s_waitcnt lgkmcnt(0)
	s_barrier
	s_setprio 1
	s_waitcnt lgkmcnt(0)
	v_mfma_f32_16x16x32_bf16 v[124:127], v[128:131], v[176:179], v[124:127]
	v_mfma_f32_16x16x32_bf16 v[120:123], v[136:139], v[176:179], v[120:123]
	v_mfma_f32_16x16x32_bf16 v[108:111], v[128:131], v[192:195], v[108:111]
	v_mfma_f32_16x16x32_bf16 v[104:107], v[136:139], v[192:195], v[104:107]
	v_mfma_f32_16x16x32_bf16 v[92:95], v[128:131], v[204:207], v[92:95]
	v_mfma_f32_16x16x32_bf16 v[88:91], v[136:139], v[204:207], v[88:91]
	v_mfma_f32_16x16x32_bf16 v[76:79], v[128:131], v[212:215], v[76:79]
	v_mfma_f32_16x16x32_bf16 v[72:75], v[136:139], v[212:215], v[72:75]
	v_mfma_f32_16x16x32_bf16 v[124:127], v[132:135], v[180:183], v[124:127]
	v_mfma_f32_16x16x32_bf16 v[120:123], v[140:143], v[180:183], v[120:123]
	v_mfma_f32_16x16x32_bf16 v[108:111], v[132:135], v[198:201], v[108:111]
	v_mfma_f32_16x16x32_bf16 v[104:107], v[140:143], v[198:201], v[104:107]
	v_mfma_f32_16x16x32_bf16 v[92:95], v[132:135], v[208:211], v[92:95]
	v_mfma_f32_16x16x32_bf16 v[88:91], v[140:143], v[208:211], v[88:91]
	v_mfma_f32_16x16x32_bf16 v[76:79], v[132:135], v[216:219], v[76:79]
	v_mfma_f32_16x16x32_bf16 v[72:75], v[140:143], v[216:219], v[72:75]
	s_setprio 0
	s_setprio 1
	v_mfma_f32_16x16x32_bf16 v[116:119], v[144:147], v[176:179], v[116:119]
	v_mfma_f32_16x16x32_bf16 v[112:115], v[168:171], v[176:179], v[112:115]
	v_mfma_f32_16x16x32_bf16 v[100:103], v[144:147], v[192:195], v[100:103]
	v_mfma_f32_16x16x32_bf16 v[96:99], v[168:171], v[192:195], v[96:99]
	v_mfma_f32_16x16x32_bf16 v[84:87], v[144:147], v[204:207], v[84:87]
	v_mfma_f32_16x16x32_bf16 v[80:83], v[168:171], v[204:207], v[80:83]
	v_mfma_f32_16x16x32_bf16 v[68:71], v[144:147], v[212:215], v[68:71]
	v_mfma_f32_16x16x32_bf16 v[64:67], v[168:171], v[212:215], v[64:67]
	v_mfma_f32_16x16x32_bf16 v[116:119], v[148:151], v[180:183], v[116:119]
	v_mfma_f32_16x16x32_bf16 v[112:115], v[172:175], v[180:183], v[112:115]
	v_mfma_f32_16x16x32_bf16 v[100:103], v[148:151], v[198:201], v[100:103]
	v_mfma_f32_16x16x32_bf16 v[96:99], v[172:175], v[198:201], v[96:99]
	v_mfma_f32_16x16x32_bf16 v[84:87], v[148:151], v[208:211], v[84:87]
	v_mfma_f32_16x16x32_bf16 v[80:83], v[172:175], v[208:211], v[80:83]
	v_mfma_f32_16x16x32_bf16 v[68:71], v[148:151], v[216:219], v[68:71]
	v_mfma_f32_16x16x32_bf16 v[64:67], v[172:175], v[216:219], v[64:67]
	s_setprio 0
	s_barrier
	s_add_i32 s59, s52, s45
	v_lshl_add_u64 v[184:185], s[4:5], 0, v[154:155]
	s_mov_b32 m0, s59
	ds_read_b128 v[176:179], v191 offset:16384
	ds_read_b128 v[180:183], v191 offset:17408
	ds_read_b128 v[192:195], v191 offset:18432
	ds_read_b128 v[198:201], v191 offset:19456
	ds_read_b128 v[204:207], v191 offset:20480
	ds_read_b128 v[208:211], v191 offset:21504
	ds_read_b128 v[212:215], v191 offset:22528
	ds_read_b128 v[216:219], v191 offset:23552
	global_load_lds_dwordx4 v[184:185], off
	s_add_i32 m0, s59, 0x2000
	s_add_u32 s60, s4, 0x40000
	v_lshl_add_u64 v[220:221], s[4:5], 0, v[158:159]
	s_addc_u32 s61, s5, 0
	s_add_i32 s59, s53, s45
	global_load_lds_dwordx4 v[220:221], off
	v_lshl_add_u64 v[222:223], s[60:61], 0, v[154:155]
	s_mov_b32 m0, s59
	v_lshl_add_u64 v[224:225], s[42:43], 0, v[156:157]
	global_load_lds_dwordx4 v[222:223], off
	v_lshl_add_u64 v[222:223], s[60:61], 0, v[158:159]
	s_add_i32 m0, s59, 0x2000
	s_nop 0
	global_load_lds_dwordx4 v[222:223], off
	v_lshl_add_u64 v[222:223], s[42:43], 0, v[152:153]
	s_mov_b32 m0, s46
	s_nop 0
	global_load_lds_dwordx4 v[222:223], off
	s_mov_b32 m0, s33
	s_nop 0
	global_load_lds_dwordx4 v[224:225], off
	s_waitcnt vmcnt(8)
	s_waitcnt lgkmcnt(0)
	s_barrier
	s_setprio 1
	s_waitcnt lgkmcnt(0)
	v_mfma_f32_16x16x32_bf16 v[60:63], v[128:131], v[176:179], v[60:63]
	v_mfma_f32_16x16x32_bf16 v[56:59], v[136:139], v[176:179], v[56:59]
	v_mfma_f32_16x16x32_bf16 v[44:47], v[128:131], v[192:195], v[44:47]
	v_mfma_f32_16x16x32_bf16 v[40:43], v[136:139], v[192:195], v[40:43]
	v_mfma_f32_16x16x32_bf16 v[28:31], v[128:131], v[204:207], v[28:31]
	v_mfma_f32_16x16x32_bf16 v[24:27], v[136:139], v[204:207], v[24:27]
	v_mfma_f32_16x16x32_bf16 v[12:15], v[128:131], v[212:215], v[12:15]
	v_mfma_f32_16x16x32_bf16 v[8:11], v[136:139], v[212:215], v[8:11]
	v_mfma_f32_16x16x32_bf16 v[60:63], v[132:135], v[180:183], v[60:63]
	v_mfma_f32_16x16x32_bf16 v[56:59], v[140:143], v[180:183], v[56:59]
	v_mfma_f32_16x16x32_bf16 v[44:47], v[132:135], v[198:201], v[44:47]
	v_mfma_f32_16x16x32_bf16 v[40:43], v[140:143], v[198:201], v[40:43]
	v_mfma_f32_16x16x32_bf16 v[28:31], v[132:135], v[208:211], v[28:31]
	v_mfma_f32_16x16x32_bf16 v[24:27], v[140:143], v[208:211], v[24:27]
	v_mfma_f32_16x16x32_bf16 v[12:15], v[132:135], v[216:219], v[12:15]
	v_mfma_f32_16x16x32_bf16 v[8:11], v[140:143], v[216:219], v[8:11]
	s_setprio 0
	s_setprio 1
	v_mfma_f32_16x16x32_bf16 v[52:55], v[144:147], v[176:179], v[52:55]
	v_mfma_f32_16x16x32_bf16 v[48:51], v[168:171], v[176:179], v[48:51]
	v_mfma_f32_16x16x32_bf16 v[36:39], v[144:147], v[192:195], v[36:39]
	v_mfma_f32_16x16x32_bf16 v[32:35], v[168:171], v[192:195], v[32:35]
	v_mfma_f32_16x16x32_bf16 v[20:23], v[144:147], v[204:207], v[20:23]
	v_mfma_f32_16x16x32_bf16 v[16:19], v[168:171], v[204:207], v[16:19]
	v_mfma_f32_16x16x32_bf16 v[4:7], v[144:147], v[212:215], v[4:7]
	v_mfma_f32_16x16x32_bf16 v[0:3], v[168:171], v[212:215], v[0:3]
	v_mfma_f32_16x16x32_bf16 v[52:55], v[148:151], v[180:183], v[52:55]
	v_mfma_f32_16x16x32_bf16 v[48:51], v[172:175], v[180:183], v[48:51]
	v_mfma_f32_16x16x32_bf16 v[36:39], v[148:151], v[198:201], v[36:39]
	v_mfma_f32_16x16x32_bf16 v[32:35], v[172:175], v[198:201], v[32:35]
	v_mfma_f32_16x16x32_bf16 v[20:23], v[148:151], v[208:211], v[20:23]
	v_mfma_f32_16x16x32_bf16 v[16:19], v[172:175], v[208:211], v[16:19]
	v_mfma_f32_16x16x32_bf16 v[4:7], v[148:151], v[216:219], v[4:7]
	v_mfma_f32_16x16x32_bf16 v[0:3], v[172:175], v[216:219], v[0:3]
	s_setprio 0
	s_barrier
	s_add_i32 s59, 0, 0x18000
	s_add_i32 s60, 0, 0x1c000
	v_add_u32_e32 v140, s59, v187
	v_add_u32_e32 v172, s60, v187
	ds_read_b128 v[128:131], v140
	ds_read_b128 v[132:135], v140 offset:1024
	ds_read_b128 v[136:139], v140 offset:2048
	ds_read_b128 v[140:143], v140 offset:3072
	ds_read_b128 v[144:147], v172
	ds_read_b128 v[148:151], v172 offset:1024
	ds_read_b128 v[168:171], v172 offset:2048
	ds_read_b128 v[172:175], v172 offset:3072
	s_add_u32 s42, s42, 0x40000
	s_addc_u32 s43, s43, 0
	s_mov_b32 m0, s47
	v_lshl_add_u64 v[226:227], s[42:43], 0, v[152:153]
	ds_read_b128 v[176:179], v191 offset:32768
	ds_read_b128 v[180:183], v191 offset:33792
	ds_read_b128 v[192:195], v191 offset:34816
	ds_read_b128 v[198:201], v191 offset:35840
	ds_read_b128 v[204:207], v191 offset:36864
	ds_read_b128 v[208:211], v191 offset:37888
	ds_read_b128 v[212:215], v191 offset:38912
	ds_read_b128 v[216:219], v191 offset:39936
	global_load_lds_dwordx4 v[226:227], off
	v_lshl_add_u64 v[226:227], s[42:43], 0, v[156:157]
	s_mov_b32 m0, s48
	s_nop 0
	global_load_lds_dwordx4 v[226:227], off
	s_waitcnt vmcnt(8)
	s_waitcnt lgkmcnt(0)
	s_barrier
	s_setprio 1
	s_waitcnt lgkmcnt(0)
	v_mfma_f32_16x16x32_bf16 v[124:127], v[128:131], v[176:179], v[124:127]
	v_mfma_f32_16x16x32_bf16 v[120:123], v[136:139], v[176:179], v[120:123]
	v_mfma_f32_16x16x32_bf16 v[108:111], v[128:131], v[192:195], v[108:111]
	v_mfma_f32_16x16x32_bf16 v[104:107], v[136:139], v[192:195], v[104:107]
	v_mfma_f32_16x16x32_bf16 v[92:95], v[128:131], v[204:207], v[92:95]
	v_mfma_f32_16x16x32_bf16 v[88:91], v[136:139], v[204:207], v[88:91]
	v_mfma_f32_16x16x32_bf16 v[76:79], v[128:131], v[212:215], v[76:79]
	v_mfma_f32_16x16x32_bf16 v[72:75], v[136:139], v[212:215], v[72:75]
	v_mfma_f32_16x16x32_bf16 v[124:127], v[132:135], v[180:183], v[124:127]
	v_mfma_f32_16x16x32_bf16 v[120:123], v[140:143], v[180:183], v[120:123]
	v_mfma_f32_16x16x32_bf16 v[108:111], v[132:135], v[198:201], v[108:111]
	v_mfma_f32_16x16x32_bf16 v[104:107], v[140:143], v[198:201], v[104:107]
	v_mfma_f32_16x16x32_bf16 v[92:95], v[132:135], v[208:211], v[92:95]
	v_mfma_f32_16x16x32_bf16 v[88:91], v[140:143], v[208:211], v[88:91]
	v_mfma_f32_16x16x32_bf16 v[76:79], v[132:135], v[216:219], v[76:79]
	v_mfma_f32_16x16x32_bf16 v[72:75], v[140:143], v[216:219], v[72:75]
	s_setprio 0
	s_setprio 1
	v_mfma_f32_16x16x32_bf16 v[116:119], v[144:147], v[176:179], v[116:119]
	v_mfma_f32_16x16x32_bf16 v[112:115], v[168:171], v[176:179], v[112:115]
	v_mfma_f32_16x16x32_bf16 v[100:103], v[144:147], v[192:195], v[100:103]
	v_mfma_f32_16x16x32_bf16 v[96:99], v[168:171], v[192:195], v[96:99]
	v_mfma_f32_16x16x32_bf16 v[84:87], v[144:147], v[204:207], v[84:87]
	v_mfma_f32_16x16x32_bf16 v[80:83], v[168:171], v[204:207], v[80:83]
	v_mfma_f32_16x16x32_bf16 v[68:71], v[144:147], v[212:215], v[68:71]
	v_mfma_f32_16x16x32_bf16 v[64:67], v[168:171], v[212:215], v[64:67]
	v_mfma_f32_16x16x32_bf16 v[116:119], v[148:151], v[180:183], v[116:119]
	v_mfma_f32_16x16x32_bf16 v[112:115], v[172:175], v[180:183], v[112:115]
	v_mfma_f32_16x16x32_bf16 v[100:103], v[148:151], v[198:201], v[100:103]
	v_mfma_f32_16x16x32_bf16 v[96:99], v[172:175], v[198:201], v[96:99]
	v_mfma_f32_16x16x32_bf16 v[84:87], v[148:151], v[208:211], v[84:87]
	v_mfma_f32_16x16x32_bf16 v[80:83], v[172:175], v[208:211], v[80:83]
	v_mfma_f32_16x16x32_bf16 v[68:71], v[148:151], v[216:219], v[68:71]
	v_mfma_f32_16x16x32_bf16 v[64:67], v[172:175], v[216:219], v[64:67]
	s_setprio 0
	s_barrier
	s_add_i32 s42, s59, s45
	v_lshl_add_u64 v[184:185], v[184:185], 0, s[26:27]
	s_mov_b32 m0, s42
	ds_read_b128 v[176:179], v191 offset:49152
	ds_read_b128 v[180:183], v191 offset:50176
	ds_read_b128 v[192:195], v191 offset:51200
	ds_read_b128 v[198:201], v191 offset:52224
	ds_read_b128 v[204:207], v191 offset:53248
	ds_read_b128 v[208:211], v191 offset:54272
	ds_read_b128 v[212:215], v191 offset:55296
	ds_read_b128 v[216:219], v191 offset:56320
	global_load_lds_dwordx4 v[184:185], off
	s_add_i32 m0, s42, 0x2000
	s_add_u32 s4, s4, 0x40080
	v_lshl_add_u64 v[184:185], v[220:221], 0, s[26:27]
	s_addc_u32 s5, s5, 0
	s_add_i32 s42, s60, s45
	global_load_lds_dwordx4 v[184:185], off
	v_lshl_add_u64 v[184:185], s[4:5], 0, v[154:155]
	s_mov_b32 m0, s42
	s_nop 0
	global_load_lds_dwordx4 v[184:185], off
	v_lshl_add_u64 v[184:185], s[4:5], 0, v[158:159]
	s_add_i32 m0, s42, 0x2000
	s_nop 0
	global_load_lds_dwordx4 v[184:185], off
	v_lshl_add_u64 v[184:185], v[222:223], 0, s[26:27]
	s_mov_b32 m0, s50
	s_nop 0
	global_load_lds_dwordx4 v[184:185], off
	v_lshl_add_u64 v[184:185], v[224:225], 0, s[26:27]
	s_mov_b32 m0, s51
	s_nop 0
	global_load_lds_dwordx4 v[184:185], off
	s_waitcnt vmcnt(8)
	s_waitcnt lgkmcnt(0)
	s_barrier
	s_setprio 1
	s_waitcnt lgkmcnt(0)
	v_mfma_f32_16x16x32_bf16 v[60:63], v[128:131], v[176:179], v[60:63]
	v_mfma_f32_16x16x32_bf16 v[56:59], v[136:139], v[176:179], v[56:59]
	v_mfma_f32_16x16x32_bf16 v[44:47], v[128:131], v[192:195], v[44:47]
	v_mfma_f32_16x16x32_bf16 v[40:43], v[136:139], v[192:195], v[40:43]
	v_mfma_f32_16x16x32_bf16 v[28:31], v[128:131], v[204:207], v[28:31]
	v_mfma_f32_16x16x32_bf16 v[24:27], v[136:139], v[204:207], v[24:27]
	v_mfma_f32_16x16x32_bf16 v[12:15], v[128:131], v[212:215], v[12:15]
	v_mfma_f32_16x16x32_bf16 v[8:11], v[136:139], v[212:215], v[8:11]
	v_mfma_f32_16x16x32_bf16 v[60:63], v[132:135], v[180:183], v[60:63]
	v_mfma_f32_16x16x32_bf16 v[56:59], v[140:143], v[180:183], v[56:59]
	v_mfma_f32_16x16x32_bf16 v[44:47], v[132:135], v[198:201], v[44:47]
	v_mfma_f32_16x16x32_bf16 v[40:43], v[140:143], v[198:201], v[40:43]
	v_mfma_f32_16x16x32_bf16 v[28:31], v[132:135], v[208:211], v[28:31]
	v_mfma_f32_16x16x32_bf16 v[24:27], v[140:143], v[208:211], v[24:27]
	v_mfma_f32_16x16x32_bf16 v[12:15], v[132:135], v[216:219], v[12:15]
	v_mfma_f32_16x16x32_bf16 v[8:11], v[140:143], v[216:219], v[8:11]
	s_setprio 0
	s_setprio 1
	v_mfma_f32_16x16x32_bf16 v[52:55], v[144:147], v[176:179], v[52:55]
	v_mfma_f32_16x16x32_bf16 v[48:51], v[168:171], v[176:179], v[48:51]
	v_mfma_f32_16x16x32_bf16 v[36:39], v[144:147], v[192:195], v[36:39]
	v_mfma_f32_16x16x32_bf16 v[32:35], v[168:171], v[192:195], v[32:35]
	v_mfma_f32_16x16x32_bf16 v[20:23], v[144:147], v[204:207], v[20:23]
	v_mfma_f32_16x16x32_bf16 v[16:19], v[168:171], v[204:207], v[16:19]
	v_mfma_f32_16x16x32_bf16 v[4:7], v[144:147], v[212:215], v[4:7]
	v_mfma_f32_16x16x32_bf16 v[0:3], v[168:171], v[212:215], v[0:3]
	v_mfma_f32_16x16x32_bf16 v[52:55], v[148:151], v[180:183], v[52:55]
	v_mfma_f32_16x16x32_bf16 v[48:51], v[172:175], v[180:183], v[48:51]
	v_mfma_f32_16x16x32_bf16 v[36:39], v[148:151], v[198:201], v[36:39]
	v_mfma_f32_16x16x32_bf16 v[32:35], v[172:175], v[198:201], v[32:35]
	v_mfma_f32_16x16x32_bf16 v[20:23], v[148:151], v[208:211], v[20:23]
	v_mfma_f32_16x16x32_bf16 v[16:19], v[172:175], v[208:211], v[16:19]
	v_mfma_f32_16x16x32_bf16 v[4:7], v[148:151], v[216:219], v[4:7]
	v_mfma_f32_16x16x32_bf16 v[0:3], v[172:175], v[216:219], v[0:3]
	s_setprio 0
	s_add_i32 s58, s58, 2
	s_add_u32 s22, s22, 0x100
	s_addc_u32 s23, s23, 0
	s_add_u32 s56, s56, 0x100
	s_addc_u32 s57, s57, 0
	s_cmp_gt_u32 s58, 13
	s_barrier
	s_cbranch_scc0 .LBB0_966
	s_and_b64 vcc, exec, s[28:29]
	s_cbranch_vccz .LBB0_969
	s_barrier

.LBB0_1048:
	ds_read_b128 v[146:149], v169
	ds_read_b128 v[150:153], v169 offset:1024
	ds_read_b128 v[154:157], v169 offset:2048
	ds_read_b128 v[160:163], v169 offset:3072
	ds_read_b128 v[178:181], v171
	ds_read_b128 v[182:185], v171 offset:1024
	ds_read_b128 v[186:189], v171 offset:2048
	ds_read_b128 v[190:193], v171 offset:3072
	s_add_u32 s4, s10, 0xfffc0080
	s_addc_u32 s5, s11, -1
	s_cmp_eq_u32 s55, 12
	s_cselect_b32 s13, s9, s5
	s_cselect_b32 s12, s31, s4
	s_cselect_b32 s5, s29, s54
	s_cselect_b32 s4, s52, s53
	v_lshl_add_u64 v[194:195], s[10:11], 0, v[138:139]
	s_add_i32 m0, s41, 0xc000
	ds_read_b128 v[198:201], v173
	ds_read_b128 v[204:207], v173 offset:1024
	ds_read_b128 v[208:211], v173 offset:2048
	ds_read_b128 v[212:215], v173 offset:3072
	ds_read_b128 v[216:219], v173 offset:4096
	ds_read_b128 v[220:223], v173 offset:5120
	ds_read_b128 v[224:227], v173 offset:6144
	ds_read_b128 v[228:231], v173 offset:7168
	global_load_lds_dwordx4 v[194:195], off
	v_lshl_add_u64 v[194:195], s[10:11], 0, v[140:141]
	s_add_i32 m0, s41, 0xe000
	s_nop 0
	global_load_lds_dwordx4 v[194:195], off
	s_waitcnt vmcnt(8)
	s_waitcnt lgkmcnt(0)
	s_barrier
	s_setprio 1
	s_waitcnt lgkmcnt(0)
	v_mfma_f32_16x16x32_bf16 v[124:127], v[146:149], v[198:201], v[124:127]
	v_mfma_f32_16x16x32_bf16 v[116:119], v[154:157], v[198:201], v[116:119]
	v_mfma_f32_16x16x32_bf16 v[108:111], v[146:149], v[208:211], v[108:111]
	v_mfma_f32_16x16x32_bf16 v[100:103], v[154:157], v[208:211], v[100:103]
	v_mfma_f32_16x16x32_bf16 v[92:95], v[146:149], v[216:219], v[92:95]
	v_mfma_f32_16x16x32_bf16 v[84:87], v[154:157], v[216:219], v[84:87]
	v_mfma_f32_16x16x32_bf16 v[76:79], v[146:149], v[224:227], v[76:79]
	v_mfma_f32_16x16x32_bf16 v[68:71], v[154:157], v[224:227], v[68:71]
	v_mfma_f32_16x16x32_bf16 v[124:127], v[150:153], v[204:207], v[124:127]
	v_mfma_f32_16x16x32_bf16 v[116:119], v[160:163], v[204:207], v[116:119]
	v_mfma_f32_16x16x32_bf16 v[108:111], v[150:153], v[212:215], v[108:111]
	v_mfma_f32_16x16x32_bf16 v[100:103], v[160:163], v[212:215], v[100:103]
	v_mfma_f32_16x16x32_bf16 v[92:95], v[150:153], v[220:223], v[92:95]
	v_mfma_f32_16x16x32_bf16 v[84:87], v[160:163], v[220:223], v[84:87]
	v_mfma_f32_16x16x32_bf16 v[76:79], v[150:153], v[228:231], v[76:79]
	v_mfma_f32_16x16x32_bf16 v[68:71], v[160:163], v[228:231], v[68:71]
	s_setprio 0
	s_setprio 1
	v_mfma_f32_16x16x32_bf16 v[120:123], v[178:181], v[198:201], v[120:123]
	v_mfma_f32_16x16x32_bf16 v[112:115], v[186:189], v[198:201], v[112:115]
	v_mfma_f32_16x16x32_bf16 v[104:107], v[178:181], v[208:211], v[104:107]
	v_mfma_f32_16x16x32_bf16 v[96:99], v[186:189], v[208:211], v[96:99]
	v_mfma_f32_16x16x32_bf16 v[88:91], v[178:181], v[216:219], v[88:91]
	v_mfma_f32_16x16x32_bf16 v[80:83], v[186:189], v[216:219], v[80:83]
	v_mfma_f32_16x16x32_bf16 v[72:75], v[178:181], v[224:227], v[72:75]
	v_mfma_f32_16x16x32_bf16 v[64:67], v[186:189], v[224:227], v[64:67]
	v_mfma_f32_16x16x32_bf16 v[120:123], v[182:185], v[204:207], v[120:123]
	v_mfma_f32_16x16x32_bf16 v[112:115], v[190:193], v[204:207], v[112:115]
	v_mfma_f32_16x16x32_bf16 v[104:107], v[182:185], v[212:215], v[104:107]
	v_mfma_f32_16x16x32_bf16 v[96:99], v[190:193], v[212:215], v[96:99]
	v_mfma_f32_16x16x32_bf16 v[88:91], v[182:185], v[220:223], v[88:91]
	v_mfma_f32_16x16x32_bf16 v[80:83], v[190:193], v[220:223], v[80:83]
	v_mfma_f32_16x16x32_bf16 v[72:75], v[182:185], v[228:231], v[72:75]
	v_mfma_f32_16x16x32_bf16 v[64:67], v[190:193], v[228:231], v[64:67]
	s_setprio 0
	s_barrier
	s_add_i32 s56, s48, s39
	v_lshl_add_u64 v[194:195], s[4:5], 0, v[132:133]
	s_mov_b32 m0, s56
	ds_read_b128 v[198:201], v173 offset:16384
	ds_read_b128 v[204:207], v173 offset:17408
	ds_read_b128 v[208:211], v173 offset:18432
	ds_read_b128 v[212:215], v173 offset:19456
	ds_read_b128 v[216:219], v173 offset:20480
	ds_read_b128 v[220:223], v173 offset:21504
	ds_read_b128 v[224:227], v173 offset:22528
	ds_read_b128 v[228:231], v173 offset:23552
	global_load_lds_dwordx4 v[194:195], off
	s_add_i32 m0, s56, 0x2000
	s_add_u32 s56, s4, 0x40000
	v_lshl_add_u64 v[232:233], s[4:5], 0, v[128:129]
	s_addc_u32 s57, s5, 0
	s_add_i32 s58, s49, s39
	global_load_lds_dwordx4 v[232:233], off
	v_lshl_add_u64 v[234:235], s[56:57], 0, v[132:133]
	s_mov_b32 m0, s58
	v_lshl_add_u64 v[236:237], s[12:13], 0, v[130:131]
	global_load_lds_dwordx4 v[234:235], off
	v_lshl_add_u64 v[234:235], s[56:57], 0, v[128:129]
	s_add_i32 m0, s58, 0x2000
	s_nop 0
	global_load_lds_dwordx4 v[234:235], off
	v_lshl_add_u64 v[234:235], s[12:13], 0, v[134:135]
	s_mov_b32 m0, s41
	s_nop 0
	global_load_lds_dwordx4 v[234:235], off
	s_mov_b32 m0, s42
	s_nop 0
	global_load_lds_dwordx4 v[236:237], off
	s_waitcnt vmcnt(8)
	s_waitcnt lgkmcnt(0)
	s_barrier
	s_setprio 1
	s_waitcnt lgkmcnt(0)
	v_mfma_f32_16x16x32_bf16 v[60:63], v[146:149], v[198:201], v[60:63]
	v_mfma_f32_16x16x32_bf16 v[52:55], v[154:157], v[198:201], v[52:55]
	v_mfma_f32_16x16x32_bf16 v[44:47], v[146:149], v[208:211], v[44:47]
	v_mfma_f32_16x16x32_bf16 v[36:39], v[154:157], v[208:211], v[36:39]
	v_mfma_f32_16x16x32_bf16 v[28:31], v[146:149], v[216:219], v[28:31]
	v_mfma_f32_16x16x32_bf16 v[20:23], v[154:157], v[216:219], v[20:23]
	v_mfma_f32_16x16x32_bf16 v[12:15], v[146:149], v[224:227], v[12:15]
	v_mfma_f32_16x16x32_bf16 v[4:7], v[154:157], v[224:227], v[4:7]
	v_mfma_f32_16x16x32_bf16 v[60:63], v[150:153], v[204:207], v[60:63]
	v_mfma_f32_16x16x32_bf16 v[52:55], v[160:163], v[204:207], v[52:55]
	v_mfma_f32_16x16x32_bf16 v[44:47], v[150:153], v[212:215], v[44:47]
	v_mfma_f32_16x16x32_bf16 v[36:39], v[160:163], v[212:215], v[36:39]
	v_mfma_f32_16x16x32_bf16 v[28:31], v[150:153], v[220:223], v[28:31]
	v_mfma_f32_16x16x32_bf16 v[20:23], v[160:163], v[220:223], v[20:23]
	v_mfma_f32_16x16x32_bf16 v[12:15], v[150:153], v[228:231], v[12:15]
	v_mfma_f32_16x16x32_bf16 v[4:7], v[160:163], v[228:231], v[4:7]
	s_setprio 0
	s_setprio 1
	v_mfma_f32_16x16x32_bf16 v[56:59], v[178:181], v[198:201], v[56:59]
	v_mfma_f32_16x16x32_bf16 v[48:51], v[186:189], v[198:201], v[48:51]
	v_mfma_f32_16x16x32_bf16 v[40:43], v[178:181], v[208:211], v[40:43]
	v_mfma_f32_16x16x32_bf16 v[32:35], v[186:189], v[208:211], v[32:35]
	v_mfma_f32_16x16x32_bf16 v[24:27], v[178:181], v[216:219], v[24:27]
	v_mfma_f32_16x16x32_bf16 v[16:19], v[186:189], v[216:219], v[16:19]
	v_mfma_f32_16x16x32_bf16 v[8:11], v[178:181], v[224:227], v[8:11]
	v_mfma_f32_16x16x32_bf16 v[0:3], v[186:189], v[224:227], v[0:3]
	v_mfma_f32_16x16x32_bf16 v[56:59], v[182:185], v[204:207], v[56:59]
	v_mfma_f32_16x16x32_bf16 v[48:51], v[190:193], v[204:207], v[48:51]
	v_mfma_f32_16x16x32_bf16 v[40:43], v[182:185], v[212:215], v[40:43]
	v_mfma_f32_16x16x32_bf16 v[32:35], v[190:193], v[212:215], v[32:35]
	v_mfma_f32_16x16x32_bf16 v[24:27], v[182:185], v[220:223], v[24:27]
	v_mfma_f32_16x16x32_bf16 v[16:19], v[190:193], v[220:223], v[16:19]
	v_mfma_f32_16x16x32_bf16 v[8:11], v[182:185], v[228:231], v[8:11]
	v_mfma_f32_16x16x32_bf16 v[0:3], v[190:193], v[228:231], v[0:3]
	s_setprio 0
	s_barrier
	s_add_i32 s56, 0, 0x18000
	v_add_u32_e32 v158, s56, v165
	s_add_i32 s57, 0, 0x1c000
	ds_read_b128 v[146:149], v158
	ds_read_b128 v[150:153], v158 offset:1024
	ds_read_b128 v[154:157], v158 offset:2048
	ds_read_b128 v[160:163], v158 offset:3072
	v_add_u32_e32 v158, s57, v165
	ds_read_b128 v[178:181], v158
	ds_read_b128 v[182:185], v158 offset:1024
	ds_read_b128 v[186:189], v158 offset:2048
	ds_read_b128 v[190:193], v158 offset:3072
	s_add_u32 s12, s12, 0x40000
	s_addc_u32 s13, s13, 0
	s_mov_b32 m0, s43
	v_lshl_add_u64 v[238:239], s[12:13], 0, v[134:135]
	ds_read_b128 v[198:201], v173 offset:32768
	ds_read_b128 v[204:207], v173 offset:33792
	ds_read_b128 v[208:211], v173 offset:34816
	ds_read_b128 v[212:215], v173 offset:35840
	ds_read_b128 v[216:219], v173 offset:36864
	ds_read_b128 v[220:223], v173 offset:37888
	ds_read_b128 v[224:227], v173 offset:38912
	ds_read_b128 v[228:231], v173 offset:39936
	global_load_lds_dwordx4 v[238:239], off
	v_lshl_add_u64 v[238:239], s[12:13], 0, v[130:131]
	s_mov_b32 m0, s44
	s_nop 0
	global_load_lds_dwordx4 v[238:239], off
	s_waitcnt vmcnt(8)
	s_waitcnt lgkmcnt(0)
	s_barrier
	s_setprio 1
	s_waitcnt lgkmcnt(0)
	v_mfma_f32_16x16x32_bf16 v[124:127], v[146:149], v[198:201], v[124:127]
	v_mfma_f32_16x16x32_bf16 v[116:119], v[154:157], v[198:201], v[116:119]
	v_mfma_f32_16x16x32_bf16 v[108:111], v[146:149], v[208:211], v[108:111]
	v_mfma_f32_16x16x32_bf16 v[100:103], v[154:157], v[208:211], v[100:103]
	v_mfma_f32_16x16x32_bf16 v[92:95], v[146:149], v[216:219], v[92:95]
	v_mfma_f32_16x16x32_bf16 v[84:87], v[154:157], v[216:219], v[84:87]
	v_mfma_f32_16x16x32_bf16 v[76:79], v[146:149], v[224:227], v[76:79]
	v_mfma_f32_16x16x32_bf16 v[68:71], v[154:157], v[224:227], v[68:71]
	v_mfma_f32_16x16x32_bf16 v[124:127], v[150:153], v[204:207], v[124:127]
	v_mfma_f32_16x16x32_bf16 v[116:119], v[160:163], v[204:207], v[116:119]
	v_mfma_f32_16x16x32_bf16 v[108:111], v[150:153], v[212:215], v[108:111]
	v_mfma_f32_16x16x32_bf16 v[100:103], v[160:163], v[212:215], v[100:103]
	v_mfma_f32_16x16x32_bf16 v[92:95], v[150:153], v[220:223], v[92:95]
	v_mfma_f32_16x16x32_bf16 v[84:87], v[160:163], v[220:223], v[84:87]
	v_mfma_f32_16x16x32_bf16 v[76:79], v[150:153], v[228:231], v[76:79]
	v_mfma_f32_16x16x32_bf16 v[68:71], v[160:163], v[228:231], v[68:71]
	s_setprio 0
	s_setprio 1
	v_mfma_f32_16x16x32_bf16 v[120:123], v[178:181], v[198:201], v[120:123]
	v_mfma_f32_16x16x32_bf16 v[112:115], v[186:189], v[198:201], v[112:115]
	v_mfma_f32_16x16x32_bf16 v[104:107], v[178:181], v[208:211], v[104:107]
	v_mfma_f32_16x16x32_bf16 v[96:99], v[186:189], v[208:211], v[96:99]
	v_mfma_f32_16x16x32_bf16 v[88:91], v[178:181], v[216:219], v[88:91]
	v_mfma_f32_16x16x32_bf16 v[80:83], v[186:189], v[216:219], v[80:83]
	v_mfma_f32_16x16x32_bf16 v[72:75], v[178:181], v[224:227], v[72:75]
	v_mfma_f32_16x16x32_bf16 v[64:67], v[186:189], v[224:227], v[64:67]
	v_mfma_f32_16x16x32_bf16 v[120:123], v[182:185], v[204:207], v[120:123]
	v_mfma_f32_16x16x32_bf16 v[112:115], v[190:193], v[204:207], v[112:115]
	v_mfma_f32_16x16x32_bf16 v[104:107], v[182:185], v[212:215], v[104:107]
	v_mfma_f32_16x16x32_bf16 v[96:99], v[190:193], v[212:215], v[96:99]
	v_mfma_f32_16x16x32_bf16 v[88:91], v[182:185], v[220:223], v[88:91]
	v_mfma_f32_16x16x32_bf16 v[80:83], v[190:193], v[220:223], v[80:83]
	v_mfma_f32_16x16x32_bf16 v[72:75], v[182:185], v[228:231], v[72:75]
	v_mfma_f32_16x16x32_bf16 v[64:67], v[190:193], v[228:231], v[64:67]
	s_setprio 0
	s_barrier
	s_add_i32 s12, s56, s39
	v_lshl_add_u64 v[194:195], v[194:195], 0, s[24:25]
	s_mov_b32 m0, s12
	ds_read_b128 v[198:201], v173 offset:49152
	ds_read_b128 v[204:207], v173 offset:50176
	ds_read_b128 v[208:211], v173 offset:51200
	ds_read_b128 v[212:215], v173 offset:52224
	ds_read_b128 v[216:219], v173 offset:53248
	ds_read_b128 v[220:223], v173 offset:54272
	ds_read_b128 v[224:227], v173 offset:55296
	ds_read_b128 v[228:231], v173 offset:56320
	global_load_lds_dwordx4 v[194:195], off
	s_add_i32 m0, s12, 0x2000
	s_add_u32 s4, s4, 0x40080
	v_lshl_add_u64 v[194:195], v[232:233], 0, s[24:25]
	s_addc_u32 s5, s5, 0
	s_add_i32 s12, s57, s39
	global_load_lds_dwordx4 v[194:195], off
	v_lshl_add_u64 v[194:195], s[4:5], 0, v[132:133]
	s_mov_b32 m0, s12
	s_nop 0
	global_load_lds_dwordx4 v[194:195], off
	v_lshl_add_u64 v[194:195], s[4:5], 0, v[128:129]
	s_add_i32 m0, s12, 0x2000
	s_nop 0
	global_load_lds_dwordx4 v[194:195], off
	v_lshl_add_u64 v[194:195], v[234:235], 0, s[24:25]
	s_mov_b32 m0, s46
	s_nop 0
	global_load_lds_dwordx4 v[194:195], off
	v_lshl_add_u64 v[194:195], v[236:237], 0, s[24:25]
	s_mov_b32 m0, s47
	s_nop 0
	global_load_lds_dwordx4 v[194:195], off
	s_waitcnt vmcnt(8)
	s_waitcnt lgkmcnt(0)
	s_barrier
	s_setprio 1
	s_waitcnt lgkmcnt(0)
	v_mfma_f32_16x16x32_bf16 v[60:63], v[146:149], v[198:201], v[60:63]
	v_mfma_f32_16x16x32_bf16 v[52:55], v[154:157], v[198:201], v[52:55]
	v_mfma_f32_16x16x32_bf16 v[44:47], v[146:149], v[208:211], v[44:47]
	v_mfma_f32_16x16x32_bf16 v[36:39], v[154:157], v[208:211], v[36:39]
	v_mfma_f32_16x16x32_bf16 v[28:31], v[146:149], v[216:219], v[28:31]
	v_mfma_f32_16x16x32_bf16 v[20:23], v[154:157], v[216:219], v[20:23]
	v_mfma_f32_16x16x32_bf16 v[12:15], v[146:149], v[224:227], v[12:15]
	v_mfma_f32_16x16x32_bf16 v[4:7], v[154:157], v[224:227], v[4:7]
	v_mfma_f32_16x16x32_bf16 v[60:63], v[150:153], v[204:207], v[60:63]
	v_mfma_f32_16x16x32_bf16 v[52:55], v[160:163], v[204:207], v[52:55]
	v_mfma_f32_16x16x32_bf16 v[44:47], v[150:153], v[212:215], v[44:47]
	v_mfma_f32_16x16x32_bf16 v[36:39], v[160:163], v[212:215], v[36:39]
	v_mfma_f32_16x16x32_bf16 v[28:31], v[150:153], v[220:223], v[28:31]
	v_mfma_f32_16x16x32_bf16 v[20:23], v[160:163], v[220:223], v[20:23]
	v_mfma_f32_16x16x32_bf16 v[12:15], v[150:153], v[228:231], v[12:15]
	v_mfma_f32_16x16x32_bf16 v[4:7], v[160:163], v[228:231], v[4:7]
	s_setprio 0
	s_setprio 1
	v_mfma_f32_16x16x32_bf16 v[56:59], v[178:181], v[198:201], v[56:59]
	v_mfma_f32_16x16x32_bf16 v[48:51], v[186:189], v[198:201], v[48:51]
	v_mfma_f32_16x16x32_bf16 v[40:43], v[178:181], v[208:211], v[40:43]
	v_mfma_f32_16x16x32_bf16 v[32:35], v[186:189], v[208:211], v[32:35]
	v_mfma_f32_16x16x32_bf16 v[24:27], v[178:181], v[216:219], v[24:27]
	v_mfma_f32_16x16x32_bf16 v[16:19], v[186:189], v[216:219], v[16:19]
	v_mfma_f32_16x16x32_bf16 v[8:11], v[178:181], v[224:227], v[8:11]
	v_mfma_f32_16x16x32_bf16 v[0:3], v[186:189], v[224:227], v[0:3]
	v_mfma_f32_16x16x32_bf16 v[56:59], v[182:185], v[204:207], v[56:59]
	v_mfma_f32_16x16x32_bf16 v[48:51], v[190:193], v[204:207], v[48:51]
	v_mfma_f32_16x16x32_bf16 v[40:43], v[182:185], v[212:215], v[40:43]
	v_mfma_f32_16x16x32_bf16 v[32:35], v[190:193], v[212:215], v[32:35]
	v_mfma_f32_16x16x32_bf16 v[24:27], v[182:185], v[220:223], v[24:27]
	v_mfma_f32_16x16x32_bf16 v[16:19], v[190:193], v[220:223], v[16:19]
	v_mfma_f32_16x16x32_bf16 v[8:11], v[182:185], v[228:231], v[8:11]
	v_mfma_f32_16x16x32_bf16 v[0:3], v[190:193], v[228:231], v[0:3]
	s_setprio 0
	s_add_i32 s55, s55, 2
	s_add_u32 s10, s10, 0x100
	s_addc_u32 s11, s11, 0
	s_add_u32 s53, s53, 0x100
	s_addc_u32 s54, s54, 0
	s_cmp_gt_u32 s55, 13
	s_barrier
	s_cbranch_scc0 .LBB0_1048
	s_and_b64 vcc, exec, s[26:27]
	s_cbranch_vccz .LBB0_1051
	s_barrier

.LBB0_1124:
	ds_read_b128 v[128:131], v189
	ds_read_b128 v[132:135], v189 offset:1024
	ds_read_b128 v[136:139], v189 offset:2048
	ds_read_b128 v[140:143], v189 offset:3072
	ds_read_b128 v[144:147], v190
	ds_read_b128 v[148:151], v190 offset:1024
	ds_read_b128 v[168:171], v190 offset:2048
	ds_read_b128 v[172:175], v190 offset:3072
	s_add_u32 s34, s30, 0x100
	s_addc_u32 s35, s31, 0
	s_cmp_eq_u32 s56, 40
	s_cselect_b32 s39, s9, s35
	s_cselect_b32 s38, s8, s34
	s_cselect_b32 s37, s29, s55
	s_cselect_b32 s36, s28, s54
	v_lshl_add_u64 v[184:185], s[30:31], 0, v[160:161]
	s_add_i32 m0, s42, 0xc000
	ds_read_b128 v[176:179], v191
	ds_read_b128 v[180:183], v191 offset:1024
	ds_read_b128 v[192:195], v191 offset:2048
	ds_read_b128 v[198:201], v191 offset:3072
	ds_read_b128 v[204:207], v191 offset:4096
	ds_read_b128 v[208:211], v191 offset:5120
	ds_read_b128 v[212:215], v191 offset:6144
	ds_read_b128 v[216:219], v191 offset:7168
	global_load_lds_dwordx4 v[184:185], off
	v_lshl_add_u64 v[184:185], s[30:31], 0, v[162:163]
	s_add_i32 m0, s42, 0xe000
	s_nop 0
	global_load_lds_dwordx4 v[184:185], off
	s_waitcnt vmcnt(8)
	s_waitcnt lgkmcnt(0)
	s_barrier
	s_setprio 1
	s_waitcnt lgkmcnt(0)
	v_mfma_f32_16x16x32_bf16 v[124:127], v[128:131], v[176:179], v[124:127]
	v_mfma_f32_16x16x32_bf16 v[120:123], v[136:139], v[176:179], v[120:123]
	v_mfma_f32_16x16x32_bf16 v[108:111], v[128:131], v[192:195], v[108:111]
	v_mfma_f32_16x16x32_bf16 v[104:107], v[136:139], v[192:195], v[104:107]
	v_mfma_f32_16x16x32_bf16 v[92:95], v[128:131], v[204:207], v[92:95]
	v_mfma_f32_16x16x32_bf16 v[88:91], v[136:139], v[204:207], v[88:91]
	v_mfma_f32_16x16x32_bf16 v[76:79], v[128:131], v[212:215], v[76:79]
	v_mfma_f32_16x16x32_bf16 v[72:75], v[136:139], v[212:215], v[72:75]
	v_mfma_f32_16x16x32_bf16 v[124:127], v[132:135], v[180:183], v[124:127]
	v_mfma_f32_16x16x32_bf16 v[120:123], v[140:143], v[180:183], v[120:123]
	v_mfma_f32_16x16x32_bf16 v[108:111], v[132:135], v[198:201], v[108:111]
	v_mfma_f32_16x16x32_bf16 v[104:107], v[140:143], v[198:201], v[104:107]
	v_mfma_f32_16x16x32_bf16 v[92:95], v[132:135], v[208:211], v[92:95]
	v_mfma_f32_16x16x32_bf16 v[88:91], v[140:143], v[208:211], v[88:91]
	v_mfma_f32_16x16x32_bf16 v[76:79], v[132:135], v[216:219], v[76:79]
	v_mfma_f32_16x16x32_bf16 v[72:75], v[140:143], v[216:219], v[72:75]
	s_setprio 0
	s_setprio 1
	v_mfma_f32_16x16x32_bf16 v[116:119], v[144:147], v[176:179], v[116:119]
	v_mfma_f32_16x16x32_bf16 v[112:115], v[168:171], v[176:179], v[112:115]
	v_mfma_f32_16x16x32_bf16 v[100:103], v[144:147], v[192:195], v[100:103]
	v_mfma_f32_16x16x32_bf16 v[96:99], v[168:171], v[192:195], v[96:99]
	v_mfma_f32_16x16x32_bf16 v[84:87], v[144:147], v[204:207], v[84:87]
	v_mfma_f32_16x16x32_bf16 v[80:83], v[168:171], v[204:207], v[80:83]
	v_mfma_f32_16x16x32_bf16 v[68:71], v[144:147], v[212:215], v[68:71]
	v_mfma_f32_16x16x32_bf16 v[64:67], v[168:171], v[212:215], v[64:67]
	v_mfma_f32_16x16x32_bf16 v[116:119], v[148:151], v[180:183], v[116:119]
	v_mfma_f32_16x16x32_bf16 v[112:115], v[172:175], v[180:183], v[112:115]
	v_mfma_f32_16x16x32_bf16 v[100:103], v[148:151], v[198:201], v[100:103]
	v_mfma_f32_16x16x32_bf16 v[96:99], v[172:175], v[198:201], v[96:99]
	v_mfma_f32_16x16x32_bf16 v[84:87], v[148:151], v[208:211], v[84:87]
	v_mfma_f32_16x16x32_bf16 v[80:83], v[172:175], v[208:211], v[80:83]
	v_mfma_f32_16x16x32_bf16 v[68:71], v[148:151], v[216:219], v[68:71]
	v_mfma_f32_16x16x32_bf16 v[64:67], v[172:175], v[216:219], v[64:67]
	s_setprio 0
	s_barrier
	s_add_i32 s30, s48, s41
	v_lshl_add_u64 v[184:185], s[36:37], 0, v[154:155]
	s_mov_b32 m0, s30
	ds_read_b128 v[176:179], v191 offset:16384
	ds_read_b128 v[180:183], v191 offset:17408
	ds_read_b128 v[192:195], v191 offset:18432
	ds_read_b128 v[198:201], v191 offset:19456
	ds_read_b128 v[204:207], v191 offset:20480
	ds_read_b128 v[208:211], v191 offset:21504
	ds_read_b128 v[212:215], v191 offset:22528
	ds_read_b128 v[216:219], v191 offset:23552
	global_load_lds_dwordx4 v[184:185], off
	s_add_i32 m0, s30, 0x2000
	s_add_u32 s30, s36, 0xb0000
	v_lshl_add_u64 v[220:221], s[36:37], 0, v[158:159]
	s_addc_u32 s31, s37, 0
	s_add_i32 s57, s49, s41
	global_load_lds_dwordx4 v[220:221], off
	v_lshl_add_u64 v[222:223], s[30:31], 0, v[154:155]
	s_mov_b32 m0, s57
	v_lshl_add_u64 v[224:225], s[38:39], 0, v[156:157]
	global_load_lds_dwordx4 v[222:223], off
	v_lshl_add_u64 v[222:223], s[30:31], 0, v[158:159]
	s_add_i32 m0, s57, 0x2000
	s_nop 0
	global_load_lds_dwordx4 v[222:223], off
	v_lshl_add_u64 v[222:223], s[38:39], 0, v[152:153]
	s_mov_b32 m0, s42
	s_nop 0
	global_load_lds_dwordx4 v[222:223], off
	s_mov_b32 m0, s33
	s_nop 0
	global_load_lds_dwordx4 v[224:225], off
	s_waitcnt vmcnt(8)
	s_waitcnt lgkmcnt(0)
	s_barrier
	s_setprio 1
	s_waitcnt lgkmcnt(0)
	v_mfma_f32_16x16x32_bf16 v[60:63], v[128:131], v[176:179], v[60:63]
	v_mfma_f32_16x16x32_bf16 v[56:59], v[136:139], v[176:179], v[56:59]
	v_mfma_f32_16x16x32_bf16 v[44:47], v[128:131], v[192:195], v[44:47]
	v_mfma_f32_16x16x32_bf16 v[40:43], v[136:139], v[192:195], v[40:43]
	v_mfma_f32_16x16x32_bf16 v[28:31], v[128:131], v[204:207], v[28:31]
	v_mfma_f32_16x16x32_bf16 v[24:27], v[136:139], v[204:207], v[24:27]
	v_mfma_f32_16x16x32_bf16 v[12:15], v[128:131], v[212:215], v[12:15]
	v_mfma_f32_16x16x32_bf16 v[8:11], v[136:139], v[212:215], v[8:11]
	v_mfma_f32_16x16x32_bf16 v[60:63], v[132:135], v[180:183], v[60:63]
	v_mfma_f32_16x16x32_bf16 v[56:59], v[140:143], v[180:183], v[56:59]
	v_mfma_f32_16x16x32_bf16 v[44:47], v[132:135], v[198:201], v[44:47]
	v_mfma_f32_16x16x32_bf16 v[40:43], v[140:143], v[198:201], v[40:43]
	v_mfma_f32_16x16x32_bf16 v[28:31], v[132:135], v[208:211], v[28:31]
	v_mfma_f32_16x16x32_bf16 v[24:27], v[140:143], v[208:211], v[24:27]
	v_mfma_f32_16x16x32_bf16 v[12:15], v[132:135], v[216:219], v[12:15]
	v_mfma_f32_16x16x32_bf16 v[8:11], v[140:143], v[216:219], v[8:11]
	s_setprio 0
	s_setprio 1
	v_mfma_f32_16x16x32_bf16 v[52:55], v[144:147], v[176:179], v[52:55]
	v_mfma_f32_16x16x32_bf16 v[48:51], v[168:171], v[176:179], v[48:51]
	v_mfma_f32_16x16x32_bf16 v[36:39], v[144:147], v[192:195], v[36:39]
	v_mfma_f32_16x16x32_bf16 v[32:35], v[168:171], v[192:195], v[32:35]
	v_mfma_f32_16x16x32_bf16 v[20:23], v[144:147], v[204:207], v[20:23]
	v_mfma_f32_16x16x32_bf16 v[16:19], v[168:171], v[204:207], v[16:19]
	v_mfma_f32_16x16x32_bf16 v[4:7], v[144:147], v[212:215], v[4:7]
	v_mfma_f32_16x16x32_bf16 v[0:3], v[168:171], v[212:215], v[0:3]
	v_mfma_f32_16x16x32_bf16 v[52:55], v[148:151], v[180:183], v[52:55]
	v_mfma_f32_16x16x32_bf16 v[48:51], v[172:175], v[180:183], v[48:51]
	v_mfma_f32_16x16x32_bf16 v[36:39], v[148:151], v[198:201], v[36:39]
	v_mfma_f32_16x16x32_bf16 v[32:35], v[172:175], v[198:201], v[32:35]
	v_mfma_f32_16x16x32_bf16 v[20:23], v[148:151], v[208:211], v[20:23]
	v_mfma_f32_16x16x32_bf16 v[16:19], v[172:175], v[208:211], v[16:19]
	v_mfma_f32_16x16x32_bf16 v[4:7], v[148:151], v[216:219], v[4:7]
	v_mfma_f32_16x16x32_bf16 v[0:3], v[172:175], v[216:219], v[0:3]
	s_setprio 0
	s_barrier
	s_add_i32 s57, 0, 0x18000
	s_add_i32 s58, 0, 0x1c000
	v_add_u32_e32 v140, s57, v187
	v_add_u32_e32 v172, s58, v187
	ds_read_b128 v[128:131], v140
	ds_read_b128 v[132:135], v140 offset:1024
	ds_read_b128 v[136:139], v140 offset:2048
	ds_read_b128 v[140:143], v140 offset:3072
	ds_read_b128 v[144:147], v172
	ds_read_b128 v[148:151], v172 offset:1024
	ds_read_b128 v[168:171], v172 offset:2048
	ds_read_b128 v[172:175], v172 offset:3072
	s_add_u32 s30, s38, 0xb0000
	s_addc_u32 s31, s39, 0
	s_mov_b32 m0, s43
	v_lshl_add_u64 v[226:227], s[30:31], 0, v[152:153]
	ds_read_b128 v[176:179], v191 offset:32768
	ds_read_b128 v[180:183], v191 offset:33792
	ds_read_b128 v[192:195], v191 offset:34816
	ds_read_b128 v[198:201], v191 offset:35840
	ds_read_b128 v[204:207], v191 offset:36864
	ds_read_b128 v[208:211], v191 offset:37888
	ds_read_b128 v[212:215], v191 offset:38912
	ds_read_b128 v[216:219], v191 offset:39936
	global_load_lds_dwordx4 v[226:227], off
	v_lshl_add_u64 v[226:227], s[30:31], 0, v[156:157]
	s_mov_b32 m0, s44
	s_nop 0
	global_load_lds_dwordx4 v[226:227], off
	s_waitcnt vmcnt(8)
	s_waitcnt lgkmcnt(0)
	s_barrier
	s_setprio 1
	s_waitcnt lgkmcnt(0)
	v_mfma_f32_16x16x32_bf16 v[124:127], v[128:131], v[176:179], v[124:127]
	v_mfma_f32_16x16x32_bf16 v[120:123], v[136:139], v[176:179], v[120:123]
	v_mfma_f32_16x16x32_bf16 v[108:111], v[128:131], v[192:195], v[108:111]
	v_mfma_f32_16x16x32_bf16 v[104:107], v[136:139], v[192:195], v[104:107]
	v_mfma_f32_16x16x32_bf16 v[92:95], v[128:131], v[204:207], v[92:95]
	v_mfma_f32_16x16x32_bf16 v[88:91], v[136:139], v[204:207], v[88:91]
	v_mfma_f32_16x16x32_bf16 v[76:79], v[128:131], v[212:215], v[76:79]
	v_mfma_f32_16x16x32_bf16 v[72:75], v[136:139], v[212:215], v[72:75]
	v_mfma_f32_16x16x32_bf16 v[124:127], v[132:135], v[180:183], v[124:127]
	v_mfma_f32_16x16x32_bf16 v[120:123], v[140:143], v[180:183], v[120:123]
	v_mfma_f32_16x16x32_bf16 v[108:111], v[132:135], v[198:201], v[108:111]
	v_mfma_f32_16x16x32_bf16 v[104:107], v[140:143], v[198:201], v[104:107]
	v_mfma_f32_16x16x32_bf16 v[92:95], v[132:135], v[208:211], v[92:95]
	v_mfma_f32_16x16x32_bf16 v[88:91], v[140:143], v[208:211], v[88:91]
	v_mfma_f32_16x16x32_bf16 v[76:79], v[132:135], v[216:219], v[76:79]
	v_mfma_f32_16x16x32_bf16 v[72:75], v[140:143], v[216:219], v[72:75]
	s_setprio 0
	s_setprio 1
	v_mfma_f32_16x16x32_bf16 v[116:119], v[144:147], v[176:179], v[116:119]
	v_mfma_f32_16x16x32_bf16 v[112:115], v[168:171], v[176:179], v[112:115]
	v_mfma_f32_16x16x32_bf16 v[100:103], v[144:147], v[192:195], v[100:103]
	v_mfma_f32_16x16x32_bf16 v[96:99], v[168:171], v[192:195], v[96:99]
	v_mfma_f32_16x16x32_bf16 v[84:87], v[144:147], v[204:207], v[84:87]
	v_mfma_f32_16x16x32_bf16 v[80:83], v[168:171], v[204:207], v[80:83]
	v_mfma_f32_16x16x32_bf16 v[68:71], v[144:147], v[212:215], v[68:71]
	v_mfma_f32_16x16x32_bf16 v[64:67], v[168:171], v[212:215], v[64:67]
	v_mfma_f32_16x16x32_bf16 v[116:119], v[148:151], v[180:183], v[116:119]
	v_mfma_f32_16x16x32_bf16 v[112:115], v[172:175], v[180:183], v[112:115]
	v_mfma_f32_16x16x32_bf16 v[100:103], v[148:151], v[198:201], v[100:103]
	v_mfma_f32_16x16x32_bf16 v[96:99], v[172:175], v[198:201], v[96:99]
	v_mfma_f32_16x16x32_bf16 v[84:87], v[148:151], v[208:211], v[84:87]
	v_mfma_f32_16x16x32_bf16 v[80:83], v[172:175], v[208:211], v[80:83]
	v_mfma_f32_16x16x32_bf16 v[68:71], v[148:151], v[216:219], v[68:71]
	v_mfma_f32_16x16x32_bf16 v[64:67], v[172:175], v[216:219], v[64:67]
	s_setprio 0
	s_barrier
	s_add_i32 s30, s57, s41
	v_lshl_add_u64 v[184:185], v[184:185], 0, s[24:25]
	s_mov_b32 m0, s30
	ds_read_b128 v[176:179], v191 offset:49152
	ds_read_b128 v[180:183], v191 offset:50176
	ds_read_b128 v[192:195], v191 offset:51200
	ds_read_b128 v[198:201], v191 offset:52224
	ds_read_b128 v[204:207], v191 offset:53248
	ds_read_b128 v[208:211], v191 offset:54272
	ds_read_b128 v[212:215], v191 offset:55296
	ds_read_b128 v[216:219], v191 offset:56320
	global_load_lds_dwordx4 v[184:185], off
	s_add_i32 m0, s30, 0x2000
	s_add_u32 s30, s36, 0xb0080
	v_lshl_add_u64 v[184:185], v[220:221], 0, s[24:25]
	s_addc_u32 s31, s37, 0
	s_add_i32 s36, s58, s41
	global_load_lds_dwordx4 v[184:185], off
	v_lshl_add_u64 v[184:185], s[30:31], 0, v[154:155]
	s_mov_b32 m0, s36
	s_nop 0
	global_load_lds_dwordx4 v[184:185], off
	v_lshl_add_u64 v[184:185], s[30:31], 0, v[158:159]
	s_add_i32 m0, s36, 0x2000
	s_nop 0
	global_load_lds_dwordx4 v[184:185], off
	v_lshl_add_u64 v[184:185], v[222:223], 0, s[24:25]
	s_mov_b32 m0, s46
	s_nop 0
	global_load_lds_dwordx4 v[184:185], off
	v_lshl_add_u64 v[184:185], v[224:225], 0, s[24:25]
	s_mov_b32 m0, s47
	s_nop 0
	global_load_lds_dwordx4 v[184:185], off
	s_waitcnt vmcnt(8)
	s_waitcnt lgkmcnt(0)
	s_barrier
	s_setprio 1
	s_waitcnt lgkmcnt(0)
	v_mfma_f32_16x16x32_bf16 v[60:63], v[128:131], v[176:179], v[60:63]
	v_mfma_f32_16x16x32_bf16 v[56:59], v[136:139], v[176:179], v[56:59]
	v_mfma_f32_16x16x32_bf16 v[44:47], v[128:131], v[192:195], v[44:47]
	v_mfma_f32_16x16x32_bf16 v[40:43], v[136:139], v[192:195], v[40:43]
	v_mfma_f32_16x16x32_bf16 v[28:31], v[128:131], v[204:207], v[28:31]
	v_mfma_f32_16x16x32_bf16 v[24:27], v[136:139], v[204:207], v[24:27]
	v_mfma_f32_16x16x32_bf16 v[12:15], v[128:131], v[212:215], v[12:15]
	v_mfma_f32_16x16x32_bf16 v[8:11], v[136:139], v[212:215], v[8:11]
	v_mfma_f32_16x16x32_bf16 v[60:63], v[132:135], v[180:183], v[60:63]
	v_mfma_f32_16x16x32_bf16 v[56:59], v[140:143], v[180:183], v[56:59]
	v_mfma_f32_16x16x32_bf16 v[44:47], v[132:135], v[198:201], v[44:47]
	v_mfma_f32_16x16x32_bf16 v[40:43], v[140:143], v[198:201], v[40:43]
	v_mfma_f32_16x16x32_bf16 v[28:31], v[132:135], v[208:211], v[28:31]
	v_mfma_f32_16x16x32_bf16 v[24:27], v[140:143], v[208:211], v[24:27]
	v_mfma_f32_16x16x32_bf16 v[12:15], v[132:135], v[216:219], v[12:15]
	v_mfma_f32_16x16x32_bf16 v[8:11], v[140:143], v[216:219], v[8:11]
	s_setprio 0
	s_setprio 1
	v_mfma_f32_16x16x32_bf16 v[52:55], v[144:147], v[176:179], v[52:55]
	v_mfma_f32_16x16x32_bf16 v[48:51], v[168:171], v[176:179], v[48:51]
	v_mfma_f32_16x16x32_bf16 v[36:39], v[144:147], v[192:195], v[36:39]
	v_mfma_f32_16x16x32_bf16 v[32:35], v[168:171], v[192:195], v[32:35]
	v_mfma_f32_16x16x32_bf16 v[20:23], v[144:147], v[204:207], v[20:23]
	v_mfma_f32_16x16x32_bf16 v[16:19], v[168:171], v[204:207], v[16:19]
	v_mfma_f32_16x16x32_bf16 v[4:7], v[144:147], v[212:215], v[4:7]
	v_mfma_f32_16x16x32_bf16 v[0:3], v[168:171], v[212:215], v[0:3]
	v_mfma_f32_16x16x32_bf16 v[52:55], v[148:151], v[180:183], v[52:55]
	v_mfma_f32_16x16x32_bf16 v[48:51], v[172:175], v[180:183], v[48:51]
	v_mfma_f32_16x16x32_bf16 v[36:39], v[148:151], v[198:201], v[36:39]
	v_mfma_f32_16x16x32_bf16 v[32:35], v[172:175], v[198:201], v[32:35]
	v_mfma_f32_16x16x32_bf16 v[20:23], v[148:151], v[208:211], v[20:23]
	v_mfma_f32_16x16x32_bf16 v[16:19], v[172:175], v[208:211], v[16:19]
	v_mfma_f32_16x16x32_bf16 v[4:7], v[148:151], v[216:219], v[4:7]
	v_mfma_f32_16x16x32_bf16 v[0:3], v[172:175], v[216:219], v[0:3]
	s_setprio 0
	s_add_i32 s56, s56, 2
	s_add_u32 s54, s54, 0x100
	s_addc_u32 s55, s55, 0
	s_cmp_gt_u32 s56, 41
	s_mov_b64 s[30:31], s[34:35]
	s_barrier
	s_cbranch_scc0 .LBB0_1124
	s_and_b64 vcc, exec, s[26:27]
	s_cbranch_vccz .LBB0_1127
	s_barrier
